# K-loop MFMA blocks: drop mid-block setprio pair and the already-satisfied lgkmcnt wait after the barrier
# speedup vs baseline: 1.0215x; 1.0024x over previous
.LBB0_212:
	ds_read_b128 v[146:149], v153
	ds_read_b128 v[156:159], v153 offset:1024
	ds_read_b128 v[160:163], v153 offset:2048
	ds_read_b128 v[164:167], v153 offset:3072
	ds_read_b128 v[174:177], v154
	ds_read_b128 v[178:181], v154 offset:1024
	ds_read_b128 v[182:185], v154 offset:2048
	ds_read_b128 v[186:189], v154 offset:3072
	s_add_u32 s26, s24, 0xfffc0080
	s_addc_u32 s27, s25, -1
	s_cmp_eq_u32 s70, 12
	s_cselect_b32 s29, s17, s27
	s_cselect_b32 s28, s44, s26
	s_cselect_b32 s27, s15, s47
	s_cselect_b32 s26, s45, s46
	v_lshl_add_u64 v[168:169], s[24:25], 0, v[138:139]
	s_add_i32 m0, s23, 0xc000
	ds_read_b128 v[190:193], v155
	ds_read_b128 v[194:197], v155 offset:1024
	ds_read_b128 v[198:201], v155 offset:2048
	ds_read_b128 v[202:205], v155 offset:3072
	ds_read_b128 v[206:209], v155 offset:4096
	ds_read_b128 v[210:213], v155 offset:5120
	ds_read_b128 v[214:217], v155 offset:6144
	ds_read_b128 v[218:221], v155 offset:7168
	global_load_lds_dwordx4 v[168:169], off
	v_lshl_add_u64 v[168:169], s[24:25], 0, v[140:141]
	s_add_i32 m0, s23, 0xe000
	s_nop 0
	global_load_lds_dwordx4 v[168:169], off
	s_waitcnt vmcnt(8)
	s_waitcnt lgkmcnt(0)
	s_barrier
	s_setprio 1
	v_mfma_f32_16x16x32_bf16 v[126:129], v[146:149], v[190:193], v[126:129]
	v_mfma_f32_16x16x32_bf16 v[122:125], v[160:163], v[190:193], v[122:125]
	v_mfma_f32_16x16x32_bf16 v[118:121], v[146:149], v[198:201], v[118:121]
	v_mfma_f32_16x16x32_bf16 v[110:113], v[160:163], v[198:201], v[110:113]
	v_mfma_f32_16x16x32_bf16 v[102:105], v[146:149], v[206:209], v[102:105]
	v_mfma_f32_16x16x32_bf16 v[94:97], v[160:163], v[206:209], v[94:97]
	v_mfma_f32_16x16x32_bf16 v[86:89], v[146:149], v[214:217], v[86:89]
	v_mfma_f32_16x16x32_bf16 v[78:81], v[160:163], v[214:217], v[78:81]
	v_mfma_f32_16x16x32_bf16 v[126:129], v[156:159], v[194:197], v[126:129]
	v_mfma_f32_16x16x32_bf16 v[122:125], v[164:167], v[194:197], v[122:125]
	v_mfma_f32_16x16x32_bf16 v[118:121], v[156:159], v[202:205], v[118:121]
	v_mfma_f32_16x16x32_bf16 v[110:113], v[164:167], v[202:205], v[110:113]
	v_mfma_f32_16x16x32_bf16 v[102:105], v[156:159], v[210:213], v[102:105]
	v_mfma_f32_16x16x32_bf16 v[94:97], v[164:167], v[210:213], v[94:97]
	v_mfma_f32_16x16x32_bf16 v[86:89], v[156:159], v[218:221], v[86:89]
	v_mfma_f32_16x16x32_bf16 v[78:81], v[164:167], v[218:221], v[78:81]
	v_mfma_f32_16x16x32_bf16 v[114:117], v[174:177], v[190:193], v[114:117]
	v_mfma_f32_16x16x32_bf16 v[106:109], v[182:185], v[190:193], v[106:109]
	v_mfma_f32_16x16x32_bf16 v[98:101], v[174:177], v[198:201], v[98:101]
	v_mfma_f32_16x16x32_bf16 v[90:93], v[182:185], v[198:201], v[90:93]
	v_mfma_f32_16x16x32_bf16 v[82:85], v[174:177], v[206:209], v[82:85]
	v_mfma_f32_16x16x32_bf16 v[74:77], v[182:185], v[206:209], v[74:77]
	v_mfma_f32_16x16x32_bf16 v[70:73], v[174:177], v[214:217], v[70:73]
	v_mfma_f32_16x16x32_bf16 v[66:69], v[182:185], v[214:217], v[66:69]
	v_mfma_f32_16x16x32_bf16 v[114:117], v[178:181], v[194:197], v[114:117]
	v_mfma_f32_16x16x32_bf16 v[106:109], v[186:189], v[194:197], v[106:109]
	v_mfma_f32_16x16x32_bf16 v[98:101], v[178:181], v[202:205], v[98:101]
	v_mfma_f32_16x16x32_bf16 v[90:93], v[186:189], v[202:205], v[90:93]
	v_mfma_f32_16x16x32_bf16 v[82:85], v[178:181], v[210:213], v[82:85]
	v_mfma_f32_16x16x32_bf16 v[74:77], v[186:189], v[210:213], v[74:77]
	v_mfma_f32_16x16x32_bf16 v[70:73], v[178:181], v[218:221], v[70:73]
	v_mfma_f32_16x16x32_bf16 v[66:69], v[186:189], v[218:221], v[66:69]
	s_setprio 0
	s_barrier
	s_add_i32 s71, s40, s7
	v_lshl_add_u64 v[168:169], s[26:27], 0, v[134:135]
	s_mov_b32 m0, s71
	ds_read_b128 v[190:193], v155 offset:16384
	ds_read_b128 v[194:197], v155 offset:17408
	ds_read_b128 v[198:201], v155 offset:18432
	ds_read_b128 v[202:205], v155 offset:19456
	ds_read_b128 v[206:209], v155 offset:20480
	ds_read_b128 v[210:213], v155 offset:21504
	ds_read_b128 v[214:217], v155 offset:22528
	ds_read_b128 v[218:221], v155 offset:23552
	global_load_lds_dwordx4 v[168:169], off
	s_add_i32 m0, s71, 0x2000
	s_add_u32 s74, s26, 0x40000
	v_lshl_add_u64 v[222:223], s[26:27], 0, v[130:131]
	s_addc_u32 s75, s27, 0
	s_add_i32 s71, s41, s7
	global_load_lds_dwordx4 v[222:223], off
	v_lshl_add_u64 v[224:225], s[74:75], 0, v[134:135]
	s_mov_b32 m0, s71
	v_lshl_add_u64 v[226:227], s[28:29], 0, v[132:133]
	global_load_lds_dwordx4 v[224:225], off
	v_lshl_add_u64 v[224:225], s[74:75], 0, v[130:131]
	s_add_i32 m0, s71, 0x2000
	s_nop 0
	global_load_lds_dwordx4 v[224:225], off
	v_lshl_add_u64 v[224:225], s[28:29], 0, v[136:137]
	s_mov_b32 m0, s23
	s_nop 0
	global_load_lds_dwordx4 v[224:225], off
	s_mov_b32 m0, s31
	s_nop 0
	global_load_lds_dwordx4 v[226:227], off
	s_waitcnt vmcnt(8)
	s_waitcnt lgkmcnt(0)
	s_barrier
	s_setprio 1
	v_mfma_f32_16x16x32_bf16 v[62:65], v[146:149], v[190:193], v[62:65]
	v_mfma_f32_16x16x32_bf16 v[58:61], v[160:163], v[190:193], v[58:61]
	v_mfma_f32_16x16x32_bf16 v[54:57], v[146:149], v[198:201], v[54:57]
	v_mfma_f32_16x16x32_bf16 v[46:49], v[160:163], v[198:201], v[46:49]
	v_mfma_f32_16x16x32_bf16 v[38:41], v[146:149], v[206:209], v[38:41]
	v_mfma_f32_16x16x32_bf16 v[30:33], v[160:163], v[206:209], v[30:33]
	v_mfma_f32_16x16x32_bf16 v[22:25], v[146:149], v[214:217], v[22:25]
	v_mfma_f32_16x16x32_bf16 v[14:17], v[160:163], v[214:217], v[14:17]
	v_mfma_f32_16x16x32_bf16 v[62:65], v[156:159], v[194:197], v[62:65]
	v_mfma_f32_16x16x32_bf16 v[58:61], v[164:167], v[194:197], v[58:61]
	v_mfma_f32_16x16x32_bf16 v[54:57], v[156:159], v[202:205], v[54:57]
	v_mfma_f32_16x16x32_bf16 v[46:49], v[164:167], v[202:205], v[46:49]
	v_mfma_f32_16x16x32_bf16 v[38:41], v[156:159], v[210:213], v[38:41]
	v_mfma_f32_16x16x32_bf16 v[30:33], v[164:167], v[210:213], v[30:33]
	v_mfma_f32_16x16x32_bf16 v[22:25], v[156:159], v[218:221], v[22:25]
	v_mfma_f32_16x16x32_bf16 v[14:17], v[164:167], v[218:221], v[14:17]
	v_mfma_f32_16x16x32_bf16 v[50:53], v[174:177], v[190:193], v[50:53]
	v_mfma_f32_16x16x32_bf16 v[42:45], v[182:185], v[190:193], v[42:45]
	v_mfma_f32_16x16x32_bf16 v[34:37], v[174:177], v[198:201], v[34:37]
	v_mfma_f32_16x16x32_bf16 v[26:29], v[182:185], v[198:201], v[26:29]
	v_mfma_f32_16x16x32_bf16 v[18:21], v[174:177], v[206:209], v[18:21]
	v_mfma_f32_16x16x32_bf16 v[10:13], v[182:185], v[206:209], v[10:13]
	v_mfma_f32_16x16x32_bf16 v[6:9], v[174:177], v[214:217], v[6:9]
	v_mfma_f32_16x16x32_bf16 v[2:5], v[182:185], v[214:217], v[2:5]
	v_mfma_f32_16x16x32_bf16 v[50:53], v[178:181], v[194:197], v[50:53]
	v_mfma_f32_16x16x32_bf16 v[42:45], v[186:189], v[194:197], v[42:45]
	v_mfma_f32_16x16x32_bf16 v[34:37], v[178:181], v[202:205], v[34:37]
	v_mfma_f32_16x16x32_bf16 v[26:29], v[186:189], v[202:205], v[26:29]
	v_mfma_f32_16x16x32_bf16 v[18:21], v[178:181], v[210:213], v[18:21]
	v_mfma_f32_16x16x32_bf16 v[10:13], v[186:189], v[210:213], v[10:13]
	v_mfma_f32_16x16x32_bf16 v[6:9], v[178:181], v[218:221], v[6:9]
	v_mfma_f32_16x16x32_bf16 v[2:5], v[186:189], v[218:221], v[2:5]
	s_setprio 0
	s_barrier
	s_add_i32 s71, 0, 0x18000
	v_add_u32_e32 v1, s71, v151
	s_add_i32 s74, 0, 0x1c000
	ds_read_b128 v[146:149], v1
	ds_read_b128 v[156:159], v1 offset:1024
	ds_read_b128 v[160:163], v1 offset:2048
	ds_read_b128 v[164:167], v1 offset:3072
	v_add_u32_e32 v1, s74, v151
	ds_read_b128 v[174:177], v1
	ds_read_b128 v[178:181], v1 offset:1024
	ds_read_b128 v[182:185], v1 offset:2048
	ds_read_b128 v[186:189], v1 offset:3072
	s_add_u32 s28, s28, 0x40000
	s_addc_u32 s29, s29, 0
	s_mov_b32 m0, s34
	v_lshl_add_u64 v[228:229], s[28:29], 0, v[136:137]
	ds_read_b128 v[190:193], v155 offset:32768
	ds_read_b128 v[194:197], v155 offset:33792
	ds_read_b128 v[198:201], v155 offset:34816
	ds_read_b128 v[202:205], v155 offset:35840
	ds_read_b128 v[206:209], v155 offset:36864
	ds_read_b128 v[210:213], v155 offset:37888
	ds_read_b128 v[214:217], v155 offset:38912
	ds_read_b128 v[218:221], v155 offset:39936
	global_load_lds_dwordx4 v[228:229], off
	v_lshl_add_u64 v[228:229], s[28:29], 0, v[132:133]
	s_mov_b32 m0, s35
	s_nop 0
	global_load_lds_dwordx4 v[228:229], off
	s_waitcnt vmcnt(8)
	s_waitcnt lgkmcnt(0)
	s_barrier
	s_setprio 1
	v_mfma_f32_16x16x32_bf16 v[126:129], v[146:149], v[190:193], v[126:129]
	v_mfma_f32_16x16x32_bf16 v[122:125], v[160:163], v[190:193], v[122:125]
	v_mfma_f32_16x16x32_bf16 v[118:121], v[146:149], v[198:201], v[118:121]
	v_mfma_f32_16x16x32_bf16 v[110:113], v[160:163], v[198:201], v[110:113]
	v_mfma_f32_16x16x32_bf16 v[102:105], v[146:149], v[206:209], v[102:105]
	v_mfma_f32_16x16x32_bf16 v[94:97], v[160:163], v[206:209], v[94:97]
	v_mfma_f32_16x16x32_bf16 v[86:89], v[146:149], v[214:217], v[86:89]
	v_mfma_f32_16x16x32_bf16 v[78:81], v[160:163], v[214:217], v[78:81]
	v_mfma_f32_16x16x32_bf16 v[126:129], v[156:159], v[194:197], v[126:129]
	v_mfma_f32_16x16x32_bf16 v[122:125], v[164:167], v[194:197], v[122:125]
	v_mfma_f32_16x16x32_bf16 v[118:121], v[156:159], v[202:205], v[118:121]
	v_mfma_f32_16x16x32_bf16 v[110:113], v[164:167], v[202:205], v[110:113]
	v_mfma_f32_16x16x32_bf16 v[102:105], v[156:159], v[210:213], v[102:105]
	v_mfma_f32_16x16x32_bf16 v[94:97], v[164:167], v[210:213], v[94:97]
	v_mfma_f32_16x16x32_bf16 v[86:89], v[156:159], v[218:221], v[86:89]
	v_mfma_f32_16x16x32_bf16 v[78:81], v[164:167], v[218:221], v[78:81]
	v_mfma_f32_16x16x32_bf16 v[114:117], v[174:177], v[190:193], v[114:117]
	v_mfma_f32_16x16x32_bf16 v[106:109], v[182:185], v[190:193], v[106:109]
	v_mfma_f32_16x16x32_bf16 v[98:101], v[174:177], v[198:201], v[98:101]
	v_mfma_f32_16x16x32_bf16 v[90:93], v[182:185], v[198:201], v[90:93]
	v_mfma_f32_16x16x32_bf16 v[82:85], v[174:177], v[206:209], v[82:85]
	v_mfma_f32_16x16x32_bf16 v[74:77], v[182:185], v[206:209], v[74:77]
	v_mfma_f32_16x16x32_bf16 v[70:73], v[174:177], v[214:217], v[70:73]
	v_mfma_f32_16x16x32_bf16 v[66:69], v[182:185], v[214:217], v[66:69]
	v_mfma_f32_16x16x32_bf16 v[114:117], v[178:181], v[194:197], v[114:117]
	v_mfma_f32_16x16x32_bf16 v[106:109], v[186:189], v[194:197], v[106:109]
	v_mfma_f32_16x16x32_bf16 v[98:101], v[178:181], v[202:205], v[98:101]
	v_mfma_f32_16x16x32_bf16 v[90:93], v[186:189], v[202:205], v[90:93]
	v_mfma_f32_16x16x32_bf16 v[82:85], v[178:181], v[210:213], v[82:85]
	v_mfma_f32_16x16x32_bf16 v[74:77], v[186:189], v[210:213], v[74:77]
	v_mfma_f32_16x16x32_bf16 v[70:73], v[178:181], v[218:221], v[70:73]
	v_mfma_f32_16x16x32_bf16 v[66:69], v[186:189], v[218:221], v[66:69]
	s_setprio 0
	s_barrier
	s_add_i32 s28, s71, s7
	v_lshl_add_u64 v[168:169], v[168:169], 0, s[10:11]
	s_mov_b32 m0, s28
	ds_read_b128 v[190:193], v155 offset:49152
	ds_read_b128 v[194:197], v155 offset:50176
	ds_read_b128 v[198:201], v155 offset:51200
	ds_read_b128 v[202:205], v155 offset:52224
	ds_read_b128 v[206:209], v155 offset:53248
	ds_read_b128 v[210:213], v155 offset:54272
	ds_read_b128 v[214:217], v155 offset:55296
	ds_read_b128 v[218:221], v155 offset:56320
	global_load_lds_dwordx4 v[168:169], off
	s_add_i32 m0, s28, 0x2000
	s_add_u32 s26, s26, 0x40080
	v_lshl_add_u64 v[168:169], v[222:223], 0, s[10:11]
	s_addc_u32 s27, s27, 0
	s_add_i32 s28, s74, s7
	global_load_lds_dwordx4 v[168:169], off
	v_lshl_add_u64 v[168:169], s[26:27], 0, v[134:135]
	s_mov_b32 m0, s28
	s_nop 0
	global_load_lds_dwordx4 v[168:169], off
	v_lshl_add_u64 v[168:169], s[26:27], 0, v[130:131]
	s_add_i32 m0, s28, 0x2000
	s_nop 0
	global_load_lds_dwordx4 v[168:169], off
	v_lshl_add_u64 v[168:169], v[224:225], 0, s[10:11]
	s_mov_b32 m0, s37
	s_nop 0
	global_load_lds_dwordx4 v[168:169], off
	v_lshl_add_u64 v[168:169], v[226:227], 0, s[10:11]
	s_mov_b32 m0, s38
	s_nop 0
	global_load_lds_dwordx4 v[168:169], off
	s_waitcnt vmcnt(8)
	s_waitcnt lgkmcnt(0)
	s_barrier
	s_setprio 1
	v_mfma_f32_16x16x32_bf16 v[62:65], v[146:149], v[190:193], v[62:65]
	v_mfma_f32_16x16x32_bf16 v[58:61], v[160:163], v[190:193], v[58:61]
	v_mfma_f32_16x16x32_bf16 v[54:57], v[146:149], v[198:201], v[54:57]
	v_mfma_f32_16x16x32_bf16 v[46:49], v[160:163], v[198:201], v[46:49]
	v_mfma_f32_16x16x32_bf16 v[38:41], v[146:149], v[206:209], v[38:41]
	v_mfma_f32_16x16x32_bf16 v[30:33], v[160:163], v[206:209], v[30:33]
	v_mfma_f32_16x16x32_bf16 v[22:25], v[146:149], v[214:217], v[22:25]
	v_mfma_f32_16x16x32_bf16 v[14:17], v[160:163], v[214:217], v[14:17]
	v_mfma_f32_16x16x32_bf16 v[62:65], v[156:159], v[194:197], v[62:65]
	v_mfma_f32_16x16x32_bf16 v[58:61], v[164:167], v[194:197], v[58:61]
	v_mfma_f32_16x16x32_bf16 v[54:57], v[156:159], v[202:205], v[54:57]
	v_mfma_f32_16x16x32_bf16 v[46:49], v[164:167], v[202:205], v[46:49]
	v_mfma_f32_16x16x32_bf16 v[38:41], v[156:159], v[210:213], v[38:41]
	v_mfma_f32_16x16x32_bf16 v[30:33], v[164:167], v[210:213], v[30:33]
	v_mfma_f32_16x16x32_bf16 v[22:25], v[156:159], v[218:221], v[22:25]
	v_mfma_f32_16x16x32_bf16 v[14:17], v[164:167], v[218:221], v[14:17]
	v_mfma_f32_16x16x32_bf16 v[50:53], v[174:177], v[190:193], v[50:53]
	v_mfma_f32_16x16x32_bf16 v[42:45], v[182:185], v[190:193], v[42:45]
	v_mfma_f32_16x16x32_bf16 v[34:37], v[174:177], v[198:201], v[34:37]
	v_mfma_f32_16x16x32_bf16 v[26:29], v[182:185], v[198:201], v[26:29]
	v_mfma_f32_16x16x32_bf16 v[18:21], v[174:177], v[206:209], v[18:21]
	v_mfma_f32_16x16x32_bf16 v[10:13], v[182:185], v[206:209], v[10:13]
	v_mfma_f32_16x16x32_bf16 v[6:9], v[174:177], v[214:217], v[6:9]
	v_mfma_f32_16x16x32_bf16 v[2:5], v[182:185], v[214:217], v[2:5]
	v_mfma_f32_16x16x32_bf16 v[50:53], v[178:181], v[194:197], v[50:53]
	v_mfma_f32_16x16x32_bf16 v[42:45], v[186:189], v[194:197], v[42:45]
	v_mfma_f32_16x16x32_bf16 v[34:37], v[178:181], v[202:205], v[34:37]
	v_mfma_f32_16x16x32_bf16 v[26:29], v[186:189], v[202:205], v[26:29]
	v_mfma_f32_16x16x32_bf16 v[18:21], v[178:181], v[210:213], v[18:21]
	v_mfma_f32_16x16x32_bf16 v[10:13], v[186:189], v[210:213], v[10:13]
	v_mfma_f32_16x16x32_bf16 v[6:9], v[178:181], v[218:221], v[6:9]
	v_mfma_f32_16x16x32_bf16 v[2:5], v[186:189], v[218:221], v[2:5]
	s_setprio 0
	s_barrier
	s_add_i32 s70, s70, 2
	s_add_u32 s24, s24, 0x100
	s_addc_u32 s25, s25, 0
	s_add_u32 s46, s46, 0x100
	s_addc_u32 s47, s47, 0
	s_cmp_gt_u32 s70, 13
	s_cbranch_scc0 .LBB0_212
	s_and_b64 vcc, exec, s[12:13]
	s_cbranch_vccz .LBB0_215
	s_barrier

.LBB0_450:
	ds_read_b128 v[98:101], v213
	ds_read_b128 v[102:105], v213 offset:1024
	ds_read_b128 v[106:109], v213 offset:2048
	ds_read_b128 v[110:113], v213 offset:3072
	ds_read_b128 v[146:149], v214
	ds_read_b128 v[150:153], v214 offset:1024
	ds_read_b128 v[154:157], v214 offset:2048
	ds_read_b128 v[158:161], v214 offset:3072
	s_add_u32 s34, s30, 0xfffc0080
	s_addc_u32 s35, s31, -1
	s_cmp_eq_u32 s71, 12
	s_cselect_b32 s37, s21, s35
	s_cselect_b32 s36, s27, s34
	s_cselect_b32 s35, s19, s70
	s_cselect_b32 s34, s29, s55
	v_lshl_add_u64 v[210:211], s[30:31], 0, v[174:175]
	s_add_i32 m0, s38, 0xc000
	ds_read_b128 v[182:185], v215
	ds_read_b128 v[186:189], v215 offset:1024
	ds_read_b128 v[190:193], v215 offset:2048
	ds_read_b128 v[194:197], v215 offset:3072
	ds_read_b128 v[198:201], v215 offset:4096
	ds_read_b128 v[202:205], v215 offset:5120
	ds_read_b128 v[206:209], v215 offset:6144
	ds_read_b128 v[218:221], v215 offset:7168
	global_load_lds_dwordx4 v[210:211], off
	v_lshl_add_u64 v[210:211], s[30:31], 0, v[176:177]
	s_add_i32 m0, s38, 0xe000
	s_nop 0
	global_load_lds_dwordx4 v[210:211], off
	s_waitcnt vmcnt(8)
	s_waitcnt lgkmcnt(0)
	s_barrier
	s_setprio 1
	v_mfma_f32_16x16x32_bf16 v[142:145], v[98:101], v[182:185], v[142:145]
	v_mfma_f32_16x16x32_bf16 v[138:141], v[106:109], v[182:185], v[138:141]
	v_mfma_f32_16x16x32_bf16 v[126:129], v[98:101], v[190:193], v[126:129]
	v_mfma_f32_16x16x32_bf16 v[122:125], v[106:109], v[190:193], v[122:125]
	v_mfma_f32_16x16x32_bf16 v[94:97], v[98:101], v[198:201], v[94:97]
	v_mfma_f32_16x16x32_bf16 v[90:93], v[106:109], v[198:201], v[90:93]
	v_mfma_f32_16x16x32_bf16 v[78:81], v[98:101], v[206:209], v[78:81]
	v_mfma_f32_16x16x32_bf16 v[74:77], v[106:109], v[206:209], v[74:77]
	v_mfma_f32_16x16x32_bf16 v[142:145], v[102:105], v[186:189], v[142:145]
	v_mfma_f32_16x16x32_bf16 v[138:141], v[110:113], v[186:189], v[138:141]
	v_mfma_f32_16x16x32_bf16 v[126:129], v[102:105], v[194:197], v[126:129]
	v_mfma_f32_16x16x32_bf16 v[122:125], v[110:113], v[194:197], v[122:125]
	v_mfma_f32_16x16x32_bf16 v[94:97], v[102:105], v[202:205], v[94:97]
	v_mfma_f32_16x16x32_bf16 v[90:93], v[110:113], v[202:205], v[90:93]
	v_mfma_f32_16x16x32_bf16 v[78:81], v[102:105], v[218:221], v[78:81]
	v_mfma_f32_16x16x32_bf16 v[74:77], v[110:113], v[218:221], v[74:77]
	v_mfma_f32_16x16x32_bf16 v[134:137], v[146:149], v[182:185], v[134:137]
	v_mfma_f32_16x16x32_bf16 v[130:133], v[154:157], v[182:185], v[130:133]
	v_mfma_f32_16x16x32_bf16 v[118:121], v[146:149], v[190:193], v[118:121]
	v_mfma_f32_16x16x32_bf16 v[114:117], v[154:157], v[190:193], v[114:117]
	v_mfma_f32_16x16x32_bf16 v[86:89], v[146:149], v[198:201], v[86:89]
	v_mfma_f32_16x16x32_bf16 v[82:85], v[154:157], v[198:201], v[82:85]
	v_mfma_f32_16x16x32_bf16 v[70:73], v[146:149], v[206:209], v[70:73]
	v_mfma_f32_16x16x32_bf16 v[66:69], v[154:157], v[206:209], v[66:69]
	v_mfma_f32_16x16x32_bf16 v[134:137], v[150:153], v[186:189], v[134:137]
	v_mfma_f32_16x16x32_bf16 v[130:133], v[158:161], v[186:189], v[130:133]
	v_mfma_f32_16x16x32_bf16 v[118:121], v[150:153], v[194:197], v[118:121]
	v_mfma_f32_16x16x32_bf16 v[114:117], v[158:161], v[194:197], v[114:117]
	v_mfma_f32_16x16x32_bf16 v[86:89], v[150:153], v[202:205], v[86:89]
	v_mfma_f32_16x16x32_bf16 v[82:85], v[158:161], v[202:205], v[82:85]
	v_mfma_f32_16x16x32_bf16 v[70:73], v[150:153], v[218:221], v[70:73]
	v_mfma_f32_16x16x32_bf16 v[66:69], v[158:161], v[218:221], v[66:69]
	s_setprio 0
	s_barrier
	s_add_i32 s74, s51, s7
	v_lshl_add_u64 v[210:211], s[34:35], 0, v[164:165]
	s_mov_b32 m0, s74
	ds_read_b128 v[182:185], v215 offset:16384
	ds_read_b128 v[186:189], v215 offset:17408
	ds_read_b128 v[190:193], v215 offset:18432
	ds_read_b128 v[194:197], v215 offset:19456
	ds_read_b128 v[198:201], v215 offset:20480
	ds_read_b128 v[202:205], v215 offset:21504
	ds_read_b128 v[206:209], v215 offset:22528
	ds_read_b128 v[218:221], v215 offset:23552
	global_load_lds_dwordx4 v[210:211], off
	s_add_i32 m0, s74, 0x2000
	s_add_u32 s74, s34, 0x40000
	v_lshl_add_u64 v[222:223], s[34:35], 0, v[168:169]
	s_addc_u32 s75, s35, 0
	s_add_i32 s76, s54, s7
	global_load_lds_dwordx4 v[222:223], off
	v_lshl_add_u64 v[224:225], s[74:75], 0, v[164:165]
	s_mov_b32 m0, s76
	v_lshl_add_u64 v[226:227], s[36:37], 0, v[166:167]
	global_load_lds_dwordx4 v[224:225], off
	v_lshl_add_u64 v[224:225], s[74:75], 0, v[168:169]
	s_add_i32 m0, s76, 0x2000
	s_nop 0
	global_load_lds_dwordx4 v[224:225], off
	v_lshl_add_u64 v[224:225], s[36:37], 0, v[162:163]
	s_mov_b32 m0, s38
	s_nop 0
	global_load_lds_dwordx4 v[224:225], off
	s_mov_b32 m0, s39
	s_nop 0
	global_load_lds_dwordx4 v[226:227], off
	s_waitcnt vmcnt(8)
	s_waitcnt lgkmcnt(0)
	s_barrier
	s_setprio 1
	v_mfma_f32_16x16x32_bf16 v[62:65], v[98:101], v[182:185], v[62:65]
	v_mfma_f32_16x16x32_bf16 v[58:61], v[106:109], v[182:185], v[58:61]
	v_mfma_f32_16x16x32_bf16 v[46:49], v[98:101], v[190:193], v[46:49]
	v_mfma_f32_16x16x32_bf16 v[42:45], v[106:109], v[190:193], v[42:45]
	v_mfma_f32_16x16x32_bf16 v[30:33], v[98:101], v[198:201], v[30:33]
	v_mfma_f32_16x16x32_bf16 v[26:29], v[106:109], v[198:201], v[26:29]
	v_mfma_f32_16x16x32_bf16 v[14:17], v[98:101], v[206:209], v[14:17]
	v_mfma_f32_16x16x32_bf16 v[10:13], v[106:109], v[206:209], v[10:13]
	v_mfma_f32_16x16x32_bf16 v[62:65], v[102:105], v[186:189], v[62:65]
	v_mfma_f32_16x16x32_bf16 v[58:61], v[110:113], v[186:189], v[58:61]
	v_mfma_f32_16x16x32_bf16 v[46:49], v[102:105], v[194:197], v[46:49]
	v_mfma_f32_16x16x32_bf16 v[42:45], v[110:113], v[194:197], v[42:45]
	v_mfma_f32_16x16x32_bf16 v[30:33], v[102:105], v[202:205], v[30:33]
	v_mfma_f32_16x16x32_bf16 v[26:29], v[110:113], v[202:205], v[26:29]
	v_mfma_f32_16x16x32_bf16 v[14:17], v[102:105], v[218:221], v[14:17]
	v_mfma_f32_16x16x32_bf16 v[10:13], v[110:113], v[218:221], v[10:13]
	v_mfma_f32_16x16x32_bf16 v[54:57], v[146:149], v[182:185], v[54:57]
	v_mfma_f32_16x16x32_bf16 v[50:53], v[154:157], v[182:185], v[50:53]
	v_mfma_f32_16x16x32_bf16 v[38:41], v[146:149], v[190:193], v[38:41]
	v_mfma_f32_16x16x32_bf16 v[34:37], v[154:157], v[190:193], v[34:37]
	v_mfma_f32_16x16x32_bf16 v[22:25], v[146:149], v[198:201], v[22:25]
	v_mfma_f32_16x16x32_bf16 v[18:21], v[154:157], v[198:201], v[18:21]
	v_mfma_f32_16x16x32_bf16 v[6:9], v[146:149], v[206:209], v[6:9]
	v_mfma_f32_16x16x32_bf16 v[2:5], v[154:157], v[206:209], v[2:5]
	v_mfma_f32_16x16x32_bf16 v[54:57], v[150:153], v[186:189], v[54:57]
	v_mfma_f32_16x16x32_bf16 v[50:53], v[158:161], v[186:189], v[50:53]
	v_mfma_f32_16x16x32_bf16 v[38:41], v[150:153], v[194:197], v[38:41]
	v_mfma_f32_16x16x32_bf16 v[34:37], v[158:161], v[194:197], v[34:37]
	v_mfma_f32_16x16x32_bf16 v[22:25], v[150:153], v[202:205], v[22:25]
	v_mfma_f32_16x16x32_bf16 v[18:21], v[158:161], v[202:205], v[18:21]
	v_mfma_f32_16x16x32_bf16 v[6:9], v[150:153], v[218:221], v[6:9]
	v_mfma_f32_16x16x32_bf16 v[2:5], v[158:161], v[218:221], v[2:5]
	s_setprio 0
	s_barrier
	s_add_i32 s74, 0, 0x18000
	v_add_u32_e32 v1, s74, v173
	s_add_i32 s75, 0, 0x1c000
	ds_read_b128 v[98:101], v1
	ds_read_b128 v[102:105], v1 offset:1024
	ds_read_b128 v[106:109], v1 offset:2048
	ds_read_b128 v[110:113], v1 offset:3072
	v_add_u32_e32 v1, s75, v173
	ds_read_b128 v[146:149], v1
	ds_read_b128 v[150:153], v1 offset:1024
	ds_read_b128 v[154:157], v1 offset:2048
	ds_read_b128 v[158:161], v1 offset:3072
	s_add_u32 s36, s36, 0x40000
	s_addc_u32 s37, s37, 0
	s_mov_b32 m0, s40
	v_lshl_add_u64 v[228:229], s[36:37], 0, v[162:163]
	ds_read_b128 v[182:185], v215 offset:32768
	ds_read_b128 v[186:189], v215 offset:33792
	ds_read_b128 v[190:193], v215 offset:34816
	ds_read_b128 v[194:197], v215 offset:35840
	ds_read_b128 v[198:201], v215 offset:36864
	ds_read_b128 v[202:205], v215 offset:37888
	ds_read_b128 v[206:209], v215 offset:38912
	ds_read_b128 v[218:221], v215 offset:39936
	global_load_lds_dwordx4 v[228:229], off
	v_lshl_add_u64 v[228:229], s[36:37], 0, v[166:167]
	s_mov_b32 m0, s41
	s_nop 0
	global_load_lds_dwordx4 v[228:229], off
	s_waitcnt vmcnt(8)
	s_waitcnt lgkmcnt(0)
	s_barrier
	s_setprio 1
	v_mfma_f32_16x16x32_bf16 v[142:145], v[98:101], v[182:185], v[142:145]
	v_mfma_f32_16x16x32_bf16 v[138:141], v[106:109], v[182:185], v[138:141]
	v_mfma_f32_16x16x32_bf16 v[126:129], v[98:101], v[190:193], v[126:129]
	v_mfma_f32_16x16x32_bf16 v[122:125], v[106:109], v[190:193], v[122:125]
	v_mfma_f32_16x16x32_bf16 v[94:97], v[98:101], v[198:201], v[94:97]
	v_mfma_f32_16x16x32_bf16 v[90:93], v[106:109], v[198:201], v[90:93]
	v_mfma_f32_16x16x32_bf16 v[78:81], v[98:101], v[206:209], v[78:81]
	v_mfma_f32_16x16x32_bf16 v[74:77], v[106:109], v[206:209], v[74:77]
	v_mfma_f32_16x16x32_bf16 v[142:145], v[102:105], v[186:189], v[142:145]
	v_mfma_f32_16x16x32_bf16 v[138:141], v[110:113], v[186:189], v[138:141]
	v_mfma_f32_16x16x32_bf16 v[126:129], v[102:105], v[194:197], v[126:129]
	v_mfma_f32_16x16x32_bf16 v[122:125], v[110:113], v[194:197], v[122:125]
	v_mfma_f32_16x16x32_bf16 v[94:97], v[102:105], v[202:205], v[94:97]
	v_mfma_f32_16x16x32_bf16 v[90:93], v[110:113], v[202:205], v[90:93]
	v_mfma_f32_16x16x32_bf16 v[78:81], v[102:105], v[218:221], v[78:81]
	v_mfma_f32_16x16x32_bf16 v[74:77], v[110:113], v[218:221], v[74:77]
	v_mfma_f32_16x16x32_bf16 v[134:137], v[146:149], v[182:185], v[134:137]
	v_mfma_f32_16x16x32_bf16 v[130:133], v[154:157], v[182:185], v[130:133]
	v_mfma_f32_16x16x32_bf16 v[118:121], v[146:149], v[190:193], v[118:121]
	v_mfma_f32_16x16x32_bf16 v[114:117], v[154:157], v[190:193], v[114:117]
	v_mfma_f32_16x16x32_bf16 v[86:89], v[146:149], v[198:201], v[86:89]
	v_mfma_f32_16x16x32_bf16 v[82:85], v[154:157], v[198:201], v[82:85]
	v_mfma_f32_16x16x32_bf16 v[70:73], v[146:149], v[206:209], v[70:73]
	v_mfma_f32_16x16x32_bf16 v[66:69], v[154:157], v[206:209], v[66:69]
	v_mfma_f32_16x16x32_bf16 v[134:137], v[150:153], v[186:189], v[134:137]
	v_mfma_f32_16x16x32_bf16 v[130:133], v[158:161], v[186:189], v[130:133]
	v_mfma_f32_16x16x32_bf16 v[118:121], v[150:153], v[194:197], v[118:121]
	v_mfma_f32_16x16x32_bf16 v[114:117], v[158:161], v[194:197], v[114:117]
	v_mfma_f32_16x16x32_bf16 v[86:89], v[150:153], v[202:205], v[86:89]
	v_mfma_f32_16x16x32_bf16 v[82:85], v[158:161], v[202:205], v[82:85]
	v_mfma_f32_16x16x32_bf16 v[70:73], v[150:153], v[218:221], v[70:73]
	v_mfma_f32_16x16x32_bf16 v[66:69], v[158:161], v[218:221], v[66:69]
	s_setprio 0
	s_barrier
	s_add_i32 s36, s74, s7
	v_lshl_add_u64 v[210:211], v[210:211], 0, s[14:15]
	s_mov_b32 m0, s36
	ds_read_b128 v[182:185], v215 offset:49152
	ds_read_b128 v[186:189], v215 offset:50176
	ds_read_b128 v[190:193], v215 offset:51200
	ds_read_b128 v[194:197], v215 offset:52224
	ds_read_b128 v[198:201], v215 offset:53248
	ds_read_b128 v[202:205], v215 offset:54272
	ds_read_b128 v[206:209], v215 offset:55296
	ds_read_b128 v[218:221], v215 offset:56320
	global_load_lds_dwordx4 v[210:211], off
	s_add_i32 m0, s36, 0x2000
	s_add_u32 s34, s34, 0x40080
	v_lshl_add_u64 v[210:211], v[222:223], 0, s[14:15]
	s_addc_u32 s35, s35, 0
	s_add_i32 s36, s75, s7
	global_load_lds_dwordx4 v[210:211], off
	v_lshl_add_u64 v[210:211], s[34:35], 0, v[164:165]
	s_mov_b32 m0, s36
	s_nop 0
	global_load_lds_dwordx4 v[210:211], off
	v_lshl_add_u64 v[210:211], s[34:35], 0, v[168:169]
	s_add_i32 m0, s36, 0x2000
	s_nop 0
	global_load_lds_dwordx4 v[210:211], off
	v_lshl_add_u64 v[210:211], v[224:225], 0, s[14:15]
	s_mov_b32 m0, s47
	s_nop 0
	global_load_lds_dwordx4 v[210:211], off
	v_lshl_add_u64 v[210:211], v[226:227], 0, s[14:15]
	s_mov_b32 m0, s48
	s_nop 0
	global_load_lds_dwordx4 v[210:211], off
	s_waitcnt vmcnt(8)
	s_waitcnt lgkmcnt(0)
	s_barrier
	s_setprio 1
	v_mfma_f32_16x16x32_bf16 v[62:65], v[98:101], v[182:185], v[62:65]
	v_mfma_f32_16x16x32_bf16 v[58:61], v[106:109], v[182:185], v[58:61]
	v_mfma_f32_16x16x32_bf16 v[46:49], v[98:101], v[190:193], v[46:49]
	v_mfma_f32_16x16x32_bf16 v[42:45], v[106:109], v[190:193], v[42:45]
	v_mfma_f32_16x16x32_bf16 v[30:33], v[98:101], v[198:201], v[30:33]
	v_mfma_f32_16x16x32_bf16 v[26:29], v[106:109], v[198:201], v[26:29]
	v_mfma_f32_16x16x32_bf16 v[14:17], v[98:101], v[206:209], v[14:17]
	v_mfma_f32_16x16x32_bf16 v[10:13], v[106:109], v[206:209], v[10:13]
	v_mfma_f32_16x16x32_bf16 v[62:65], v[102:105], v[186:189], v[62:65]
	v_mfma_f32_16x16x32_bf16 v[58:61], v[110:113], v[186:189], v[58:61]
	v_mfma_f32_16x16x32_bf16 v[46:49], v[102:105], v[194:197], v[46:49]
	v_mfma_f32_16x16x32_bf16 v[42:45], v[110:113], v[194:197], v[42:45]
	v_mfma_f32_16x16x32_bf16 v[30:33], v[102:105], v[202:205], v[30:33]
	v_mfma_f32_16x16x32_bf16 v[26:29], v[110:113], v[202:205], v[26:29]
	v_mfma_f32_16x16x32_bf16 v[14:17], v[102:105], v[218:221], v[14:17]
	v_mfma_f32_16x16x32_bf16 v[10:13], v[110:113], v[218:221], v[10:13]
	v_mfma_f32_16x16x32_bf16 v[54:57], v[146:149], v[182:185], v[54:57]
	v_mfma_f32_16x16x32_bf16 v[50:53], v[154:157], v[182:185], v[50:53]
	v_mfma_f32_16x16x32_bf16 v[38:41], v[146:149], v[190:193], v[38:41]
	v_mfma_f32_16x16x32_bf16 v[34:37], v[154:157], v[190:193], v[34:37]
	v_mfma_f32_16x16x32_bf16 v[22:25], v[146:149], v[198:201], v[22:25]
	v_mfma_f32_16x16x32_bf16 v[18:21], v[154:157], v[198:201], v[18:21]
	v_mfma_f32_16x16x32_bf16 v[6:9], v[146:149], v[206:209], v[6:9]
	v_mfma_f32_16x16x32_bf16 v[2:5], v[154:157], v[206:209], v[2:5]
	v_mfma_f32_16x16x32_bf16 v[54:57], v[150:153], v[186:189], v[54:57]
	v_mfma_f32_16x16x32_bf16 v[50:53], v[158:161], v[186:189], v[50:53]
	v_mfma_f32_16x16x32_bf16 v[38:41], v[150:153], v[194:197], v[38:41]
	v_mfma_f32_16x16x32_bf16 v[34:37], v[158:161], v[194:197], v[34:37]
	v_mfma_f32_16x16x32_bf16 v[22:25], v[150:153], v[202:205], v[22:25]
	v_mfma_f32_16x16x32_bf16 v[18:21], v[158:161], v[202:205], v[18:21]
	v_mfma_f32_16x16x32_bf16 v[6:9], v[150:153], v[218:221], v[6:9]
	v_mfma_f32_16x16x32_bf16 v[2:5], v[158:161], v[218:221], v[2:5]
	s_setprio 0
	s_barrier
	s_add_i32 s71, s71, 2
	s_add_u32 s30, s30, 0x100
	s_addc_u32 s31, s31, 0
	s_add_u32 s55, s55, 0x100
	s_addc_u32 s70, s70, 0
	s_cmp_gt_u32 s71, 13
	s_cbranch_scc0 .LBB0_450
	s_and_b64 vcc, exec, s[16:17]
	s_cbranch_vccz .LBB0_453
	s_barrier

.LBB0_557:
	ds_read_b128 v[30:33], v219
	ds_read_b128 v[54:57], v219 offset:1024
	ds_read_b128 v[118:121], v219 offset:2048
	ds_read_b128 v[122:125], v219 offset:3072
	ds_read_b128 v[146:149], v220
	ds_read_b128 v[150:153], v220 offset:1024
	ds_read_b128 v[154:157], v220 offset:2048
	ds_read_b128 v[158:161], v220 offset:3072
	s_add_u32 s48, s8, 0xfffc0080
	s_addc_u32 s49, s9, -1
	s_cmp_eq_u32 s7, 12
	s_cselect_b32 s51, s41, s49
	s_cselect_b32 s50, s47, s48
	s_cselect_b32 s49, s39, s3
	s_cselect_b32 s48, vcc_lo, vcc_hi
	v_lshl_add_u64 v[232:233], s[8:9], 0, v[186:187]
	s_add_i32 m0, s70, 0xc000
	ds_read_b128 v[162:165], v221
	ds_read_b128 v[166:169], v221 offset:1024
	ds_read_b128 v[194:197], v221 offset:2048
	ds_read_b128 v[198:201], v221 offset:3072
	ds_read_b128 v[202:205], v221 offset:4096
	ds_read_b128 v[206:209], v221 offset:5120
	ds_read_b128 v[224:227], v221 offset:6144
	ds_read_b128 v[228:231], v221 offset:7168
	global_load_lds_dwordx4 v[232:233], off
	v_lshl_add_u64 v[232:233], s[8:9], 0, v[188:189]
	s_add_i32 m0, s70, 0xe000
	s_nop 0
	global_load_lds_dwordx4 v[232:233], off
	s_waitcnt vmcnt(8)
	s_waitcnt lgkmcnt(0)
	s_barrier
	s_setprio 1
	v_mfma_f32_16x16x32_bf16 v[62:65], v[30:33], v[162:165], v[62:65]
	v_mfma_f32_16x16x32_bf16 v[42:45], v[118:121], v[162:165], v[42:45]
	v_mfma_f32_16x16x32_bf16 v[50:53], v[30:33], v[194:197], v[50:53]
	v_mfma_f32_16x16x32_bf16 v[38:41], v[118:121], v[194:197], v[38:41]
	v_mfma_f32_16x16x32_bf16 v[46:49], v[30:33], v[202:205], v[46:49]
	v_mfma_f32_16x16x32_bf16 v[34:37], v[118:121], v[202:205], v[34:37]
	v_mfma_f32_16x16x32_bf16 v[142:145], v[30:33], v[224:227], v[142:145]
	v_mfma_f32_16x16x32_bf16 v[82:85], v[118:121], v[224:227], v[82:85]
	v_mfma_f32_16x16x32_bf16 v[62:65], v[54:57], v[166:169], v[62:65]
	v_mfma_f32_16x16x32_bf16 v[42:45], v[122:125], v[166:169], v[42:45]
	v_mfma_f32_16x16x32_bf16 v[50:53], v[54:57], v[198:201], v[50:53]
	v_mfma_f32_16x16x32_bf16 v[38:41], v[122:125], v[198:201], v[38:41]
	v_mfma_f32_16x16x32_bf16 v[46:49], v[54:57], v[206:209], v[46:49]
	v_mfma_f32_16x16x32_bf16 v[34:37], v[122:125], v[206:209], v[34:37]
	v_mfma_f32_16x16x32_bf16 v[142:145], v[54:57], v[228:231], v[142:145]
	v_mfma_f32_16x16x32_bf16 v[82:85], v[122:125], v[228:231], v[82:85]
	v_mfma_f32_16x16x32_bf16 v[134:137], v[146:149], v[162:165], v[134:137]
	v_mfma_f32_16x16x32_bf16 v[74:77], v[154:157], v[162:165], v[74:77]
	v_mfma_f32_16x16x32_bf16 v[130:133], v[146:149], v[194:197], v[130:133]
	v_mfma_f32_16x16x32_bf16 v[70:73], v[154:157], v[194:197], v[70:73]
	v_mfma_f32_16x16x32_bf16 v[78:81], v[146:149], v[202:205], v[78:81]
	v_mfma_f32_16x16x32_bf16 v[66:69], v[154:157], v[202:205], v[66:69]
	v_mfma_f32_16x16x32_bf16 v[138:141], v[146:149], v[224:227], v[138:141]
	v_mfma_f32_16x16x32_bf16 v[98:101], v[154:157], v[224:227], v[98:101]
	v_mfma_f32_16x16x32_bf16 v[134:137], v[150:153], v[166:169], v[134:137]
	v_mfma_f32_16x16x32_bf16 v[74:77], v[158:161], v[166:169], v[74:77]
	v_mfma_f32_16x16x32_bf16 v[130:133], v[150:153], v[198:201], v[130:133]
	v_mfma_f32_16x16x32_bf16 v[70:73], v[158:161], v[198:201], v[70:73]
	v_mfma_f32_16x16x32_bf16 v[78:81], v[150:153], v[206:209], v[78:81]
	v_mfma_f32_16x16x32_bf16 v[66:69], v[158:161], v[206:209], v[66:69]
	v_mfma_f32_16x16x32_bf16 v[138:141], v[150:153], v[228:231], v[138:141]
	v_mfma_f32_16x16x32_bf16 v[98:101], v[158:161], v[228:231], v[98:101]
	s_setprio 0
	s_barrier
	s_add_i32 s84, s93, s64
	v_lshl_add_u64 v[232:233], s[48:49], 0, v[176:177]
	s_mov_b32 m0, s84
	ds_read_b128 v[162:165], v221 offset:16384
	ds_read_b128 v[166:169], v221 offset:17408
	ds_read_b128 v[194:197], v221 offset:18432
	ds_read_b128 v[198:201], v221 offset:19456
	ds_read_b128 v[202:205], v221 offset:20480
	ds_read_b128 v[206:209], v221 offset:21504
	ds_read_b128 v[224:227], v221 offset:22528
	ds_read_b128 v[228:231], v221 offset:23552
	global_load_lds_dwordx4 v[232:233], off
	s_add_i32 m0, s84, 0x2000
	s_add_u32 s84, s48, 0x40000
	v_lshl_add_u64 v[234:235], s[48:49], 0, v[180:181]
	s_addc_u32 s85, s49, 0
	s_add_i32 s86, s90, s64
	global_load_lds_dwordx4 v[234:235], off
	v_lshl_add_u64 v[236:237], s[84:85], 0, v[176:177]
	s_mov_b32 m0, s86
	v_lshl_add_u64 v[238:239], s[50:51], 0, v[178:179]
	global_load_lds_dwordx4 v[236:237], off
	v_lshl_add_u64 v[236:237], s[84:85], 0, v[180:181]
	s_add_i32 m0, s86, 0x2000
	s_nop 0
	global_load_lds_dwordx4 v[236:237], off
	v_lshl_add_u64 v[236:237], s[50:51], 0, v[174:175]
	s_mov_b32 m0, s70
	s_nop 0
	global_load_lds_dwordx4 v[236:237], off
	s_mov_b32 m0, s71
	s_nop 0
	global_load_lds_dwordx4 v[238:239], off
	s_waitcnt vmcnt(8)
	s_waitcnt lgkmcnt(0)
	s_barrier
	s_setprio 1
	v_mfma_f32_16x16x32_bf16 v[94:97], v[30:33], v[162:165], v[94:97]
	v_mfma_f32_16x16x32_bf16 v[10:13], v[118:121], v[162:165], v[10:13]
	v_mfma_f32_16x16x32_bf16 v[90:93], v[30:33], v[194:197], v[90:93]
	v_mfma_f32_16x16x32_bf16 v[6:9], v[118:121], v[194:197], v[6:9]
	v_mfma_f32_16x16x32_bf16 v[86:89], v[30:33], v[202:205], v[86:89]
	v_mfma_f32_16x16x32_bf16 v[2:5], v[118:121], v[202:205], v[2:5]
	v_mfma_f32_16x16x32_bf16 v[26:29], v[118:121], v[224:227], v[26:29]
	v_mfma_f32_16x16x32_bf16 v[94:97], v[54:57], v[166:169], v[94:97]
	v_mfma_f32_16x16x32_bf16 v[10:13], v[122:125], v[166:169], v[10:13]
	v_mfma_f32_16x16x32_bf16 v[90:93], v[54:57], v[198:201], v[90:93]
	v_mfma_f32_16x16x32_bf16 v[6:9], v[122:125], v[198:201], v[6:9]
	v_mfma_f32_16x16x32_bf16 v[86:89], v[54:57], v[206:209], v[86:89]
	v_mfma_f32_16x16x32_bf16 v[2:5], v[122:125], v[206:209], v[2:5]
	v_mfma_f32_16x16x32_bf16 v[30:33], v[30:33], v[224:227], v[114:117]
	v_mfma_f32_16x16x32_bf16 v[26:29], v[122:125], v[228:231], v[26:29]
	v_mfma_f32_16x16x32_bf16 v[30:33], v[54:57], v[228:231], v[30:33]
	v_mfma_f32_16x16x32_bf16 v[22:25], v[154:157], v[162:165], v[22:25]
	v_mfma_f32_16x16x32_bf16 v[106:109], v[146:149], v[194:197], v[106:109]
	v_mfma_f32_16x16x32_bf16 v[18:21], v[154:157], v[194:197], v[18:21]
	v_mfma_f32_16x16x32_bf16 v[102:105], v[146:149], v[202:205], v[102:105]
	v_mfma_f32_16x16x32_bf16 v[14:17], v[154:157], v[202:205], v[14:17]
	v_mfma_f32_16x16x32_bf16 v[58:61], v[154:157], v[224:227], v[58:61]
	v_mfma_f32_16x16x32_bf16 v[54:57], v[146:149], v[162:165], v[110:113]
	v_mfma_f32_16x16x32_bf16 v[22:25], v[158:161], v[166:169], v[22:25]
	v_mfma_f32_16x16x32_bf16 v[106:109], v[150:153], v[198:201], v[106:109]
	v_mfma_f32_16x16x32_bf16 v[18:21], v[158:161], v[198:201], v[18:21]
	v_mfma_f32_16x16x32_bf16 v[102:105], v[150:153], v[206:209], v[102:105]
	v_mfma_f32_16x16x32_bf16 v[14:17], v[158:161], v[206:209], v[14:17]
	v_mfma_f32_16x16x32_bf16 v[110:113], v[146:149], v[224:227], v[126:129]
	v_mfma_f32_16x16x32_bf16 v[58:61], v[158:161], v[228:231], v[58:61]
	v_mfma_f32_16x16x32_bf16 v[54:57], v[150:153], v[166:169], v[54:57]
	v_mfma_f32_16x16x32_bf16 v[118:121], v[150:153], v[228:231], v[110:113]
	s_setprio 0
	s_barrier
	s_add_i32 s84, 0, 0x18000
	v_add_u32_e32 v1, s84, v210
	s_add_i32 s85, 0, 0x1c000
	ds_read_b128 v[110:113], v1
	ds_read_b128 v[114:117], v1 offset:1024
	ds_read_b128 v[122:125], v1 offset:2048
	ds_read_b128 v[126:129], v1 offset:3072
	v_add_u32_e32 v1, s85, v210
	ds_read_b128 v[146:149], v1
	ds_read_b128 v[150:153], v1 offset:1024
	ds_read_b128 v[154:157], v1 offset:2048
	ds_read_b128 v[158:161], v1 offset:3072
	s_add_u32 s50, s50, 0x40000
	s_addc_u32 s51, s51, 0
	s_mov_b32 m0, s74
	v_lshl_add_u64 v[240:241], s[50:51], 0, v[174:175]
	ds_read_b128 v[162:165], v221 offset:32768
	ds_read_b128 v[166:169], v221 offset:33792
	ds_read_b128 v[194:197], v221 offset:34816
	ds_read_b128 v[198:201], v221 offset:35840
	ds_read_b128 v[202:205], v221 offset:36864
	ds_read_b128 v[206:209], v221 offset:37888
	ds_read_b128 v[224:227], v221 offset:38912
	ds_read_b128 v[228:231], v221 offset:39936
	global_load_lds_dwordx4 v[240:241], off
	v_lshl_add_u64 v[240:241], s[50:51], 0, v[178:179]
	s_mov_b32 m0, s75
	s_nop 0
	global_load_lds_dwordx4 v[240:241], off
	s_waitcnt vmcnt(8)
	s_waitcnt lgkmcnt(0)
	s_barrier
	s_setprio 1
	v_mfma_f32_16x16x32_bf16 v[62:65], v[110:113], v[162:165], v[62:65]
	v_mfma_f32_16x16x32_bf16 v[42:45], v[122:125], v[162:165], v[42:45]
	v_mfma_f32_16x16x32_bf16 v[50:53], v[110:113], v[194:197], v[50:53]
	v_mfma_f32_16x16x32_bf16 v[38:41], v[122:125], v[194:197], v[38:41]
	v_mfma_f32_16x16x32_bf16 v[46:49], v[110:113], v[202:205], v[46:49]
	v_mfma_f32_16x16x32_bf16 v[34:37], v[122:125], v[202:205], v[34:37]
	v_mfma_f32_16x16x32_bf16 v[142:145], v[110:113], v[224:227], v[142:145]
	v_mfma_f32_16x16x32_bf16 v[82:85], v[122:125], v[224:227], v[82:85]
	v_mfma_f32_16x16x32_bf16 v[62:65], v[114:117], v[166:169], v[62:65]
	v_mfma_f32_16x16x32_bf16 v[42:45], v[126:129], v[166:169], v[42:45]
	v_mfma_f32_16x16x32_bf16 v[50:53], v[114:117], v[198:201], v[50:53]
	v_mfma_f32_16x16x32_bf16 v[38:41], v[126:129], v[198:201], v[38:41]
	v_mfma_f32_16x16x32_bf16 v[46:49], v[114:117], v[206:209], v[46:49]
	v_mfma_f32_16x16x32_bf16 v[34:37], v[126:129], v[206:209], v[34:37]
	v_mfma_f32_16x16x32_bf16 v[142:145], v[114:117], v[228:231], v[142:145]
	v_mfma_f32_16x16x32_bf16 v[82:85], v[126:129], v[228:231], v[82:85]
	v_mfma_f32_16x16x32_bf16 v[134:137], v[146:149], v[162:165], v[134:137]
	v_mfma_f32_16x16x32_bf16 v[74:77], v[154:157], v[162:165], v[74:77]
	v_mfma_f32_16x16x32_bf16 v[130:133], v[146:149], v[194:197], v[130:133]
	v_mfma_f32_16x16x32_bf16 v[70:73], v[154:157], v[194:197], v[70:73]
	v_mfma_f32_16x16x32_bf16 v[78:81], v[146:149], v[202:205], v[78:81]
	v_mfma_f32_16x16x32_bf16 v[66:69], v[154:157], v[202:205], v[66:69]
	v_mfma_f32_16x16x32_bf16 v[138:141], v[146:149], v[224:227], v[138:141]
	v_mfma_f32_16x16x32_bf16 v[98:101], v[154:157], v[224:227], v[98:101]
	v_mfma_f32_16x16x32_bf16 v[134:137], v[150:153], v[166:169], v[134:137]
	v_mfma_f32_16x16x32_bf16 v[74:77], v[158:161], v[166:169], v[74:77]
	v_mfma_f32_16x16x32_bf16 v[130:133], v[150:153], v[198:201], v[130:133]
	v_mfma_f32_16x16x32_bf16 v[70:73], v[158:161], v[198:201], v[70:73]
	v_mfma_f32_16x16x32_bf16 v[78:81], v[150:153], v[206:209], v[78:81]
	v_mfma_f32_16x16x32_bf16 v[66:69], v[158:161], v[206:209], v[66:69]
	v_mfma_f32_16x16x32_bf16 v[138:141], v[150:153], v[228:231], v[138:141]
	v_mfma_f32_16x16x32_bf16 v[98:101], v[158:161], v[228:231], v[98:101]
	s_setprio 0
	s_barrier
	s_add_i32 s50, s84, s64
	v_lshl_add_u64 v[232:233], v[232:233], 0, s[26:27]
	s_mov_b32 m0, s50
	ds_read_b128 v[162:165], v221 offset:49152
	ds_read_b128 v[166:169], v221 offset:50176
	ds_read_b128 v[194:197], v221 offset:51200
	ds_read_b128 v[198:201], v221 offset:52224
	ds_read_b128 v[202:205], v221 offset:53248
	ds_read_b128 v[206:209], v221 offset:54272
	ds_read_b128 v[224:227], v221 offset:55296
	ds_read_b128 v[228:231], v221 offset:56320
	global_load_lds_dwordx4 v[232:233], off
	s_add_i32 m0, s50, 0x2000
	s_add_u32 s48, s48, 0x40080
	v_lshl_add_u64 v[232:233], v[234:235], 0, s[26:27]
	s_addc_u32 s49, s49, 0
	s_add_i32 s50, s85, s64
	global_load_lds_dwordx4 v[232:233], off
	v_lshl_add_u64 v[232:233], s[48:49], 0, v[176:177]
	s_mov_b32 m0, s50
	s_nop 0
	global_load_lds_dwordx4 v[232:233], off
	v_lshl_add_u64 v[232:233], s[48:49], 0, v[180:181]
	s_add_i32 m0, s50, 0x2000
	s_nop 0
	global_load_lds_dwordx4 v[232:233], off
	v_lshl_add_u64 v[232:233], v[236:237], 0, s[26:27]
	s_mov_b32 m0, s77
	s_nop 0
	global_load_lds_dwordx4 v[232:233], off
	v_lshl_add_u64 v[232:233], v[238:239], 0, s[26:27]
	s_mov_b32 m0, s78
	s_nop 0
	global_load_lds_dwordx4 v[232:233], off
	s_waitcnt vmcnt(8)
	s_waitcnt lgkmcnt(0)
	s_barrier
	s_setprio 1
	v_mfma_f32_16x16x32_bf16 v[94:97], v[110:113], v[162:165], v[94:97]
	v_mfma_f32_16x16x32_bf16 v[10:13], v[122:125], v[162:165], v[10:13]
	v_mfma_f32_16x16x32_bf16 v[90:93], v[110:113], v[194:197], v[90:93]
	v_mfma_f32_16x16x32_bf16 v[6:9], v[122:125], v[194:197], v[6:9]
	v_mfma_f32_16x16x32_bf16 v[86:89], v[110:113], v[202:205], v[86:89]
	v_mfma_f32_16x16x32_bf16 v[2:5], v[122:125], v[202:205], v[2:5]
	v_mfma_f32_16x16x32_bf16 v[30:33], v[110:113], v[224:227], v[30:33]
	v_mfma_f32_16x16x32_bf16 v[26:29], v[122:125], v[224:227], v[26:29]
	v_mfma_f32_16x16x32_bf16 v[94:97], v[114:117], v[166:169], v[94:97]
	v_mfma_f32_16x16x32_bf16 v[10:13], v[126:129], v[166:169], v[10:13]
	v_mfma_f32_16x16x32_bf16 v[90:93], v[114:117], v[198:201], v[90:93]
	v_mfma_f32_16x16x32_bf16 v[6:9], v[126:129], v[198:201], v[6:9]
	v_mfma_f32_16x16x32_bf16 v[86:89], v[114:117], v[206:209], v[86:89]
	v_mfma_f32_16x16x32_bf16 v[2:5], v[126:129], v[206:209], v[2:5]
	v_mfma_f32_16x16x32_bf16 v[114:117], v[114:117], v[228:231], v[30:33]
	v_mfma_f32_16x16x32_bf16 v[26:29], v[126:129], v[228:231], v[26:29]
	v_mfma_f32_16x16x32_bf16 v[30:33], v[146:149], v[162:165], v[54:57]
	v_mfma_f32_16x16x32_bf16 v[110:113], v[150:153], v[166:169], v[30:33]
	v_mfma_f32_16x16x32_bf16 v[30:33], v[146:149], v[194:197], v[106:109]
	v_mfma_f32_16x16x32_bf16 v[106:109], v[150:153], v[198:201], v[30:33]
	v_mfma_f32_16x16x32_bf16 v[30:33], v[146:149], v[202:205], v[102:105]
	v_mfma_f32_16x16x32_bf16 v[102:105], v[150:153], v[206:209], v[30:33]
	v_mfma_f32_16x16x32_bf16 v[30:33], v[146:149], v[224:227], v[118:121]
	v_mfma_f32_16x16x32_bf16 v[22:25], v[154:157], v[162:165], v[22:25]
	v_mfma_f32_16x16x32_bf16 v[18:21], v[154:157], v[194:197], v[18:21]
	v_mfma_f32_16x16x32_bf16 v[14:17], v[154:157], v[202:205], v[14:17]
	v_mfma_f32_16x16x32_bf16 v[126:129], v[150:153], v[228:231], v[30:33]
	v_mfma_f32_16x16x32_bf16 v[30:33], v[154:157], v[224:227], v[58:61]
	v_mfma_f32_16x16x32_bf16 v[22:25], v[158:161], v[166:169], v[22:25]
	v_mfma_f32_16x16x32_bf16 v[18:21], v[158:161], v[198:201], v[18:21]
	v_mfma_f32_16x16x32_bf16 v[14:17], v[158:161], v[206:209], v[14:17]
	v_mfma_f32_16x16x32_bf16 v[58:61], v[158:161], v[228:231], v[30:33]
	s_setprio 0
	s_barrier
	s_add_i32 s7, s7, 2
	s_add_u32 s8, s8, 0x100
	s_addc_u32 s9, s9, 0
	s_add_u32 vcc_hi, vcc_hi, 0x100
	s_addc_u32 s3, s3, 0
	s_cmp_gt_u32 s7, 13
	s_cbranch_scc0 .LBB0_557
	s_and_b64 vcc, exec, s[14:15]
	s_cbranch_vccz .LBB0_560
	s_barrier

.LBB0_733:
	ds_read_b128 v[78:81], v184
	ds_read_b128 v[86:89], v184 offset:1024
	ds_read_b128 v[90:93], v184 offset:2048
	ds_read_b128 v[94:97], v184 offset:3072
	ds_read_b128 v[146:149], v185
	ds_read_b128 v[150:153], v185 offset:1024
	ds_read_b128 v[176:179], v185 offset:2048
	ds_read_b128 v[180:183], v185 offset:3072
	s_add_u32 s26, s24, 0xfff50080
	s_addc_u32 s27, s25, -1
	s_cmp_eq_u32 s51, 40
	s_cselect_b32 s29, s9, s27
	s_cselect_b32 s28, s8, s26
	s_cselect_b32 s27, s23, s50
	s_cselect_b32 s26, s22, s49
	v_lshl_add_u64 v[220:221], s[24:25], 0, v[162:163]
	s_add_i32 m0, s34, 0xc000
	ds_read_b128 v[188:191], v186
	ds_read_b128 v[192:195], v186 offset:1024
	ds_read_b128 v[196:199], v186 offset:2048
	ds_read_b128 v[200:203], v186 offset:3072
	ds_read_b128 v[204:207], v186 offset:4096
	ds_read_b128 v[208:211], v186 offset:5120
	ds_read_b128 v[212:215], v186 offset:6144
	ds_read_b128 v[216:219], v186 offset:7168
	global_load_lds_dwordx4 v[220:221], off
	v_lshl_add_u64 v[220:221], s[24:25], 0, v[164:165]
	s_add_i32 m0, s34, 0xe000
	s_nop 0
	global_load_lds_dwordx4 v[220:221], off
	s_waitcnt vmcnt(8)
	s_waitcnt lgkmcnt(0)
	s_barrier
	s_setprio 1
	v_mfma_f32_16x16x32_bf16 v[142:145], v[78:81], v[188:191], v[142:145]
	v_mfma_f32_16x16x32_bf16 v[138:141], v[90:93], v[188:191], v[138:141]
	v_mfma_f32_16x16x32_bf16 v[126:129], v[78:81], v[196:199], v[126:129]
	v_mfma_f32_16x16x32_bf16 v[122:125], v[90:93], v[196:199], v[122:125]
	v_mfma_f32_16x16x32_bf16 v[110:113], v[78:81], v[204:207], v[110:113]
	v_mfma_f32_16x16x32_bf16 v[106:109], v[90:93], v[204:207], v[106:109]
	v_mfma_f32_16x16x32_bf16 v[82:85], v[78:81], v[212:215], v[82:85]
	v_mfma_f32_16x16x32_bf16 v[74:77], v[90:93], v[212:215], v[74:77]
	v_mfma_f32_16x16x32_bf16 v[142:145], v[86:89], v[192:195], v[142:145]
	v_mfma_f32_16x16x32_bf16 v[138:141], v[94:97], v[192:195], v[138:141]
	v_mfma_f32_16x16x32_bf16 v[126:129], v[86:89], v[200:203], v[126:129]
	v_mfma_f32_16x16x32_bf16 v[122:125], v[94:97], v[200:203], v[122:125]
	v_mfma_f32_16x16x32_bf16 v[110:113], v[86:89], v[208:211], v[110:113]
	v_mfma_f32_16x16x32_bf16 v[106:109], v[94:97], v[208:211], v[106:109]
	v_mfma_f32_16x16x32_bf16 v[82:85], v[86:89], v[216:219], v[82:85]
	v_mfma_f32_16x16x32_bf16 v[74:77], v[94:97], v[216:219], v[74:77]
	v_mfma_f32_16x16x32_bf16 v[134:137], v[146:149], v[188:191], v[134:137]
	v_mfma_f32_16x16x32_bf16 v[130:133], v[176:179], v[188:191], v[130:133]
	v_mfma_f32_16x16x32_bf16 v[118:121], v[146:149], v[196:199], v[118:121]
	v_mfma_f32_16x16x32_bf16 v[114:117], v[176:179], v[196:199], v[114:117]
	v_mfma_f32_16x16x32_bf16 v[102:105], v[146:149], v[204:207], v[102:105]
	v_mfma_f32_16x16x32_bf16 v[98:101], v[176:179], v[204:207], v[98:101]
	v_mfma_f32_16x16x32_bf16 v[70:73], v[146:149], v[212:215], v[70:73]
	v_mfma_f32_16x16x32_bf16 v[66:69], v[176:179], v[212:215], v[66:69]
	v_mfma_f32_16x16x32_bf16 v[134:137], v[150:153], v[192:195], v[134:137]
	v_mfma_f32_16x16x32_bf16 v[130:133], v[180:183], v[192:195], v[130:133]
	v_mfma_f32_16x16x32_bf16 v[118:121], v[150:153], v[200:203], v[118:121]
	v_mfma_f32_16x16x32_bf16 v[114:117], v[180:183], v[200:203], v[114:117]
	v_mfma_f32_16x16x32_bf16 v[102:105], v[150:153], v[208:211], v[102:105]
	v_mfma_f32_16x16x32_bf16 v[98:101], v[180:183], v[208:211], v[98:101]
	v_mfma_f32_16x16x32_bf16 v[70:73], v[150:153], v[216:219], v[70:73]
	v_mfma_f32_16x16x32_bf16 v[66:69], v[180:183], v[216:219], v[66:69]
	s_setprio 0
	s_barrier
	s_add_i32 s54, s43, s31
	v_lshl_add_u64 v[220:221], s[26:27], 0, v[156:157]
	s_mov_b32 m0, s54
	ds_read_b128 v[188:191], v186 offset:16384
	ds_read_b128 v[192:195], v186 offset:17408
	ds_read_b128 v[196:199], v186 offset:18432
	ds_read_b128 v[200:203], v186 offset:19456
	ds_read_b128 v[204:207], v186 offset:20480
	ds_read_b128 v[208:211], v186 offset:21504
	ds_read_b128 v[212:215], v186 offset:22528
	ds_read_b128 v[216:219], v186 offset:23552
	global_load_lds_dwordx4 v[220:221], off
	s_add_i32 m0, s54, 0x2000
	s_add_u32 s54, s26, 0xb0000
	v_lshl_add_u64 v[222:223], s[26:27], 0, v[160:161]
	s_addc_u32 s55, s27, 0
	s_add_i32 s58, s44, s31
	global_load_lds_dwordx4 v[222:223], off
	v_lshl_add_u64 v[224:225], s[54:55], 0, v[156:157]
	s_mov_b32 m0, s58
	v_lshl_add_u64 v[226:227], s[28:29], 0, v[158:159]
	global_load_lds_dwordx4 v[224:225], off
	v_lshl_add_u64 v[224:225], s[54:55], 0, v[160:161]
	s_add_i32 m0, s58, 0x2000
	s_nop 0
	global_load_lds_dwordx4 v[224:225], off
	v_lshl_add_u64 v[224:225], s[28:29], 0, v[154:155]
	s_mov_b32 m0, s34
	s_nop 0
	global_load_lds_dwordx4 v[224:225], off
	s_mov_b32 m0, s35
	s_nop 0
	global_load_lds_dwordx4 v[226:227], off
	s_waitcnt vmcnt(8)
	s_waitcnt lgkmcnt(0)
	s_barrier
	s_setprio 1
	v_mfma_f32_16x16x32_bf16 v[62:65], v[78:81], v[188:191], v[62:65]
	v_mfma_f32_16x16x32_bf16 v[58:61], v[90:93], v[188:191], v[58:61]
	v_mfma_f32_16x16x32_bf16 v[46:49], v[78:81], v[196:199], v[46:49]
	v_mfma_f32_16x16x32_bf16 v[42:45], v[90:93], v[196:199], v[42:45]
	v_mfma_f32_16x16x32_bf16 v[30:33], v[78:81], v[204:207], v[30:33]
	v_mfma_f32_16x16x32_bf16 v[26:29], v[90:93], v[204:207], v[26:29]
	v_mfma_f32_16x16x32_bf16 v[14:17], v[78:81], v[212:215], v[14:17]
	v_mfma_f32_16x16x32_bf16 v[10:13], v[90:93], v[212:215], v[10:13]
	v_mfma_f32_16x16x32_bf16 v[62:65], v[86:89], v[192:195], v[62:65]
	v_mfma_f32_16x16x32_bf16 v[58:61], v[94:97], v[192:195], v[58:61]
	v_mfma_f32_16x16x32_bf16 v[46:49], v[86:89], v[200:203], v[46:49]
	v_mfma_f32_16x16x32_bf16 v[42:45], v[94:97], v[200:203], v[42:45]
	v_mfma_f32_16x16x32_bf16 v[30:33], v[86:89], v[208:211], v[30:33]
	v_mfma_f32_16x16x32_bf16 v[26:29], v[94:97], v[208:211], v[26:29]
	v_mfma_f32_16x16x32_bf16 v[14:17], v[86:89], v[216:219], v[14:17]
	v_mfma_f32_16x16x32_bf16 v[10:13], v[94:97], v[216:219], v[10:13]
	v_mfma_f32_16x16x32_bf16 v[54:57], v[146:149], v[188:191], v[54:57]
	v_mfma_f32_16x16x32_bf16 v[50:53], v[176:179], v[188:191], v[50:53]
	v_mfma_f32_16x16x32_bf16 v[38:41], v[146:149], v[196:199], v[38:41]
	v_mfma_f32_16x16x32_bf16 v[34:37], v[176:179], v[196:199], v[34:37]
	v_mfma_f32_16x16x32_bf16 v[22:25], v[146:149], v[204:207], v[22:25]
	v_mfma_f32_16x16x32_bf16 v[18:21], v[176:179], v[204:207], v[18:21]
	v_mfma_f32_16x16x32_bf16 v[6:9], v[146:149], v[212:215], v[6:9]
	v_mfma_f32_16x16x32_bf16 v[2:5], v[176:179], v[212:215], v[2:5]
	v_mfma_f32_16x16x32_bf16 v[54:57], v[150:153], v[192:195], v[54:57]
	v_mfma_f32_16x16x32_bf16 v[50:53], v[180:183], v[192:195], v[50:53]
	v_mfma_f32_16x16x32_bf16 v[38:41], v[150:153], v[200:203], v[38:41]
	v_mfma_f32_16x16x32_bf16 v[34:37], v[180:183], v[200:203], v[34:37]
	v_mfma_f32_16x16x32_bf16 v[22:25], v[150:153], v[208:211], v[22:25]
	v_mfma_f32_16x16x32_bf16 v[18:21], v[180:183], v[208:211], v[18:21]
	v_mfma_f32_16x16x32_bf16 v[6:9], v[150:153], v[216:219], v[6:9]
	v_mfma_f32_16x16x32_bf16 v[2:5], v[180:183], v[216:219], v[2:5]
	s_setprio 0
	s_barrier
	s_add_i32 s54, 0, 0x18000
	v_add_u32_e32 v1, s54, v173
	s_add_i32 s55, 0, 0x1c000
	ds_read_b128 v[78:81], v1
	ds_read_b128 v[86:89], v1 offset:1024
	ds_read_b128 v[90:93], v1 offset:2048
	ds_read_b128 v[94:97], v1 offset:3072
	v_add_u32_e32 v1, s55, v173
	ds_read_b128 v[146:149], v1
	ds_read_b128 v[150:153], v1 offset:1024
	ds_read_b128 v[176:179], v1 offset:2048
	ds_read_b128 v[180:183], v1 offset:3072
	s_add_u32 s28, s28, 0xb0000
	s_addc_u32 s29, s29, 0
	s_mov_b32 m0, s36
	v_lshl_add_u64 v[228:229], s[28:29], 0, v[154:155]
	ds_read_b128 v[188:191], v186 offset:32768
	ds_read_b128 v[192:195], v186 offset:33792
	ds_read_b128 v[196:199], v186 offset:34816
	ds_read_b128 v[200:203], v186 offset:35840
	ds_read_b128 v[204:207], v186 offset:36864
	ds_read_b128 v[208:211], v186 offset:37888
	ds_read_b128 v[212:215], v186 offset:38912
	ds_read_b128 v[216:219], v186 offset:39936
	global_load_lds_dwordx4 v[228:229], off
	v_lshl_add_u64 v[228:229], s[28:29], 0, v[158:159]
	s_mov_b32 m0, s37
	s_nop 0
	global_load_lds_dwordx4 v[228:229], off
	s_waitcnt vmcnt(8)
	s_waitcnt lgkmcnt(0)
	s_barrier
	s_setprio 1
	v_mfma_f32_16x16x32_bf16 v[142:145], v[78:81], v[188:191], v[142:145]
	v_mfma_f32_16x16x32_bf16 v[138:141], v[90:93], v[188:191], v[138:141]
	v_mfma_f32_16x16x32_bf16 v[126:129], v[78:81], v[196:199], v[126:129]
	v_mfma_f32_16x16x32_bf16 v[122:125], v[90:93], v[196:199], v[122:125]
	v_mfma_f32_16x16x32_bf16 v[110:113], v[78:81], v[204:207], v[110:113]
	v_mfma_f32_16x16x32_bf16 v[106:109], v[90:93], v[204:207], v[106:109]
	v_mfma_f32_16x16x32_bf16 v[82:85], v[78:81], v[212:215], v[82:85]
	v_mfma_f32_16x16x32_bf16 v[74:77], v[90:93], v[212:215], v[74:77]
	v_mfma_f32_16x16x32_bf16 v[142:145], v[86:89], v[192:195], v[142:145]
	v_mfma_f32_16x16x32_bf16 v[138:141], v[94:97], v[192:195], v[138:141]
	v_mfma_f32_16x16x32_bf16 v[126:129], v[86:89], v[200:203], v[126:129]
	v_mfma_f32_16x16x32_bf16 v[122:125], v[94:97], v[200:203], v[122:125]
	v_mfma_f32_16x16x32_bf16 v[110:113], v[86:89], v[208:211], v[110:113]
	v_mfma_f32_16x16x32_bf16 v[106:109], v[94:97], v[208:211], v[106:109]
	v_mfma_f32_16x16x32_bf16 v[82:85], v[86:89], v[216:219], v[82:85]
	v_mfma_f32_16x16x32_bf16 v[74:77], v[94:97], v[216:219], v[74:77]
	v_mfma_f32_16x16x32_bf16 v[134:137], v[146:149], v[188:191], v[134:137]
	v_mfma_f32_16x16x32_bf16 v[130:133], v[176:179], v[188:191], v[130:133]
	v_mfma_f32_16x16x32_bf16 v[118:121], v[146:149], v[196:199], v[118:121]
	v_mfma_f32_16x16x32_bf16 v[114:117], v[176:179], v[196:199], v[114:117]
	v_mfma_f32_16x16x32_bf16 v[102:105], v[146:149], v[204:207], v[102:105]
	v_mfma_f32_16x16x32_bf16 v[98:101], v[176:179], v[204:207], v[98:101]
	v_mfma_f32_16x16x32_bf16 v[70:73], v[146:149], v[212:215], v[70:73]
	v_mfma_f32_16x16x32_bf16 v[66:69], v[176:179], v[212:215], v[66:69]
	v_mfma_f32_16x16x32_bf16 v[134:137], v[150:153], v[192:195], v[134:137]
	v_mfma_f32_16x16x32_bf16 v[130:133], v[180:183], v[192:195], v[130:133]
	v_mfma_f32_16x16x32_bf16 v[118:121], v[150:153], v[200:203], v[118:121]
	v_mfma_f32_16x16x32_bf16 v[114:117], v[180:183], v[200:203], v[114:117]
	v_mfma_f32_16x16x32_bf16 v[102:105], v[150:153], v[208:211], v[102:105]
	v_mfma_f32_16x16x32_bf16 v[98:101], v[180:183], v[208:211], v[98:101]
	v_mfma_f32_16x16x32_bf16 v[70:73], v[150:153], v[216:219], v[70:73]
	v_mfma_f32_16x16x32_bf16 v[66:69], v[180:183], v[216:219], v[66:69]
	s_setprio 0
	s_barrier
	s_add_i32 s28, s54, s31
	v_lshl_add_u64 v[220:221], v[220:221], 0, s[18:19]
	s_mov_b32 m0, s28
	ds_read_b128 v[188:191], v186 offset:49152
	ds_read_b128 v[192:195], v186 offset:50176
	ds_read_b128 v[196:199], v186 offset:51200
	ds_read_b128 v[200:203], v186 offset:52224
	ds_read_b128 v[204:207], v186 offset:53248
	ds_read_b128 v[208:211], v186 offset:54272
	ds_read_b128 v[212:215], v186 offset:55296
	ds_read_b128 v[216:219], v186 offset:56320
	global_load_lds_dwordx4 v[220:221], off
	s_add_i32 m0, s28, 0x2000
	s_add_u32 s26, s26, 0xb0080
	v_lshl_add_u64 v[220:221], v[222:223], 0, s[18:19]
	s_addc_u32 s27, s27, 0
	s_add_i32 s28, s55, s31
	global_load_lds_dwordx4 v[220:221], off
	v_lshl_add_u64 v[220:221], s[26:27], 0, v[156:157]
	s_mov_b32 m0, s28
	s_nop 0
	global_load_lds_dwordx4 v[220:221], off
	v_lshl_add_u64 v[220:221], s[26:27], 0, v[160:161]
	s_add_i32 m0, s28, 0x2000
	s_nop 0
	global_load_lds_dwordx4 v[220:221], off
	v_lshl_add_u64 v[220:221], v[224:225], 0, s[18:19]
	s_mov_b32 m0, s41
	s_nop 0
	global_load_lds_dwordx4 v[220:221], off
	v_lshl_add_u64 v[220:221], v[226:227], 0, s[18:19]
	s_mov_b32 m0, s42
	s_nop 0
	global_load_lds_dwordx4 v[220:221], off
	s_waitcnt vmcnt(8)
	s_waitcnt lgkmcnt(0)
	s_barrier
	s_setprio 1
	v_mfma_f32_16x16x32_bf16 v[62:65], v[78:81], v[188:191], v[62:65]
	v_mfma_f32_16x16x32_bf16 v[58:61], v[90:93], v[188:191], v[58:61]
	v_mfma_f32_16x16x32_bf16 v[46:49], v[78:81], v[196:199], v[46:49]
	v_mfma_f32_16x16x32_bf16 v[42:45], v[90:93], v[196:199], v[42:45]
	v_mfma_f32_16x16x32_bf16 v[30:33], v[78:81], v[204:207], v[30:33]
	v_mfma_f32_16x16x32_bf16 v[26:29], v[90:93], v[204:207], v[26:29]
	v_mfma_f32_16x16x32_bf16 v[14:17], v[78:81], v[212:215], v[14:17]
	v_mfma_f32_16x16x32_bf16 v[10:13], v[90:93], v[212:215], v[10:13]
	v_mfma_f32_16x16x32_bf16 v[62:65], v[86:89], v[192:195], v[62:65]
	v_mfma_f32_16x16x32_bf16 v[58:61], v[94:97], v[192:195], v[58:61]
	v_mfma_f32_16x16x32_bf16 v[46:49], v[86:89], v[200:203], v[46:49]
	v_mfma_f32_16x16x32_bf16 v[42:45], v[94:97], v[200:203], v[42:45]
	v_mfma_f32_16x16x32_bf16 v[30:33], v[86:89], v[208:211], v[30:33]
	v_mfma_f32_16x16x32_bf16 v[26:29], v[94:97], v[208:211], v[26:29]
	v_mfma_f32_16x16x32_bf16 v[14:17], v[86:89], v[216:219], v[14:17]
	v_mfma_f32_16x16x32_bf16 v[10:13], v[94:97], v[216:219], v[10:13]
	v_mfma_f32_16x16x32_bf16 v[54:57], v[146:149], v[188:191], v[54:57]
	v_mfma_f32_16x16x32_bf16 v[50:53], v[176:179], v[188:191], v[50:53]
	v_mfma_f32_16x16x32_bf16 v[38:41], v[146:149], v[196:199], v[38:41]
	v_mfma_f32_16x16x32_bf16 v[34:37], v[176:179], v[196:199], v[34:37]
	v_mfma_f32_16x16x32_bf16 v[22:25], v[146:149], v[204:207], v[22:25]
	v_mfma_f32_16x16x32_bf16 v[18:21], v[176:179], v[204:207], v[18:21]
	v_mfma_f32_16x16x32_bf16 v[6:9], v[146:149], v[212:215], v[6:9]
	v_mfma_f32_16x16x32_bf16 v[2:5], v[176:179], v[212:215], v[2:5]
	v_mfma_f32_16x16x32_bf16 v[54:57], v[150:153], v[192:195], v[54:57]
	v_mfma_f32_16x16x32_bf16 v[50:53], v[180:183], v[192:195], v[50:53]
	v_mfma_f32_16x16x32_bf16 v[38:41], v[150:153], v[200:203], v[38:41]
	v_mfma_f32_16x16x32_bf16 v[34:37], v[180:183], v[200:203], v[34:37]
	v_mfma_f32_16x16x32_bf16 v[22:25], v[150:153], v[208:211], v[22:25]
	v_mfma_f32_16x16x32_bf16 v[18:21], v[180:183], v[208:211], v[18:21]
	v_mfma_f32_16x16x32_bf16 v[6:9], v[150:153], v[216:219], v[6:9]
	v_mfma_f32_16x16x32_bf16 v[2:5], v[180:183], v[216:219], v[2:5]
	s_setprio 0
	s_barrier
	s_add_i32 s51, s51, 2
	s_add_u32 s24, s24, 0x100
	s_addc_u32 s25, s25, 0
	s_add_u32 s49, s49, 0x100
	s_addc_u32 s50, s50, 0
	s_cmp_gt_u32 s51, 41
	s_cbranch_scc0 .LBB0_733
	s_and_b64 vcc, exec, s[20:21]
	s_cbranch_vccz .LBB0_736
	s_barrier

.LBB0_1203:
	s_ashr_i32 s35, s34, 31
	s_lshl_b64 s[36:37], s[34:35], 19
	ds_read_b128 v[2:5], v190
	ds_read_b128 v[6:9], v190 offset:1024
	ds_read_b128 v[10:13], v190 offset:2048
	ds_read_b128 v[14:17], v190 offset:3072
	ds_read_b128 v[18:21], v191
	ds_read_b128 v[22:25], v191 offset:1024
	ds_read_b128 v[26:29], v191 offset:2048
	ds_read_b128 v[30:33], v191 offset:3072
	s_add_u32 s9, s52, s36
	s_addc_u32 s35, s53, s37
	s_ashr_i32 s31, s30, 31
	s_lshl_b64 s[36:37], s[30:31], 9
	s_add_u32 s36, s9, s36
	s_addc_u32 s37, s35, s37
	s_and_b64 s[38:39], s[4:5], exec
	s_cselect_b32 s49, s37, s41
	s_cselect_b32 s48, s36, s40
	s_lshl_b64 s[38:39], s[30:31], 17
	s_add_u32 s38, s3, s38
	s_addc_u32 s39, s6, s39
	s_and_b64 s[46:47], s[4:5], exec
	s_cselect_b32 s47, s39, s45
	s_cselect_b32 s46, s38, s44
	s_add_u32 s74, s40, 0x40080
	s_addc_u32 s75, s41, 0
	s_add_i32 s77, s43, 0xc000
	v_lshl_add_u64 v[66:67], s[74:75], 0, v[146:147]
	s_mov_b32 m0, s77
	s_add_i32 s9, s43, 0xe000
	ds_read_b128 v[34:37], v192
	ds_read_b128 v[38:41], v192 offset:1024
	ds_read_b128 v[42:45], v192 offset:2048
	ds_read_b128 v[46:49], v192 offset:3072
	ds_read_b128 v[50:53], v192 offset:4096
	ds_read_b128 v[54:57], v192 offset:5120
	ds_read_b128 v[58:61], v192 offset:6144
	ds_read_b128 v[62:65], v192 offset:7168
	global_load_lds_dwordx4 v[66:67], off
	v_lshl_add_u64 v[66:67], s[74:75], 0, v[150:151]
	s_mov_b32 m0, s9
	s_nop 0
	global_load_lds_dwordx4 v[66:67], off
	s_waitcnt vmcnt(8)
	s_waitcnt lgkmcnt(0)
	s_barrier
	s_setprio 1
	v_mfma_f32_16x16x32_bf16 v[66:69], v[2:5], v[34:37], 0
	v_mfma_f32_16x16x32_bf16 v[70:73], v[10:13], v[34:37], 0
	v_mfma_f32_16x16x32_bf16 v[74:77], v[2:5], v[42:45], 0
	v_mfma_f32_16x16x32_bf16 v[78:81], v[10:13], v[42:45], 0
	v_mfma_f32_16x16x32_bf16 v[82:85], v[2:5], v[50:53], 0
	v_mfma_f32_16x16x32_bf16 v[86:89], v[10:13], v[50:53], 0
	v_mfma_f32_16x16x32_bf16 v[90:93], v[2:5], v[58:61], 0
	v_mfma_f32_16x16x32_bf16 v[94:97], v[10:13], v[58:61], 0
	v_mfma_f32_16x16x32_bf16 v[66:69], v[6:9], v[38:41], v[66:69]
	v_mfma_f32_16x16x32_bf16 v[70:73], v[14:17], v[38:41], v[70:73]
	v_mfma_f32_16x16x32_bf16 v[74:77], v[6:9], v[46:49], v[74:77]
	v_mfma_f32_16x16x32_bf16 v[78:81], v[14:17], v[46:49], v[78:81]
	v_mfma_f32_16x16x32_bf16 v[82:85], v[6:9], v[54:57], v[82:85]
	v_mfma_f32_16x16x32_bf16 v[86:89], v[14:17], v[54:57], v[86:89]
	v_mfma_f32_16x16x32_bf16 v[90:93], v[6:9], v[62:65], v[90:93]
	v_mfma_f32_16x16x32_bf16 v[94:97], v[14:17], v[62:65], v[94:97]
	v_mfma_f32_16x16x32_bf16 v[98:101], v[18:21], v[34:37], 0
	v_mfma_f32_16x16x32_bf16 v[34:37], v[26:29], v[34:37], 0
	v_mfma_f32_16x16x32_bf16 v[98:101], v[22:25], v[38:41], v[98:101]
	v_mfma_f32_16x16x32_bf16 v[34:37], v[30:33], v[38:41], v[34:37]
	v_mfma_f32_16x16x32_bf16 v[38:41], v[18:21], v[42:45], 0
	v_mfma_f32_16x16x32_bf16 v[42:45], v[26:29], v[42:45], 0
	v_mfma_f32_16x16x32_bf16 v[38:41], v[22:25], v[46:49], v[38:41]
	v_mfma_f32_16x16x32_bf16 v[42:45], v[30:33], v[46:49], v[42:45]
	v_mfma_f32_16x16x32_bf16 v[46:49], v[18:21], v[50:53], 0
	v_mfma_f32_16x16x32_bf16 v[50:53], v[26:29], v[50:53], 0
	v_mfma_f32_16x16x32_bf16 v[46:49], v[22:25], v[54:57], v[46:49]
	v_mfma_f32_16x16x32_bf16 v[50:53], v[30:33], v[54:57], v[50:53]
	v_mfma_f32_16x16x32_bf16 v[54:57], v[18:21], v[58:61], 0
	v_mfma_f32_16x16x32_bf16 v[58:61], v[26:29], v[58:61], 0
	v_mfma_f32_16x16x32_bf16 v[54:57], v[22:25], v[62:65], v[54:57]
	v_mfma_f32_16x16x32_bf16 v[58:61], v[30:33], v[62:65], v[58:61]
	s_setprio 0
	s_barrier
	s_add_i32 s75, s72, s7
	v_lshl_add_u64 v[188:189], s[44:45], 0, v[148:149]
	s_add_i32 s31, s75, 0x2000
	v_lshl_add_u64 v[130:131], v[188:189], 0, s[26:27]
	s_mov_b32 m0, s75
	v_lshl_add_u64 v[218:219], s[44:45], 0, v[152:153]
	s_add_u32 s78, s44, 0x10100
	ds_read_b128 v[62:65], v192 offset:16384
	ds_read_b128 v[102:105], v192 offset:17408
	ds_read_b128 v[106:109], v192 offset:18432
	ds_read_b128 v[110:113], v192 offset:19456
	ds_read_b128 v[114:117], v192 offset:20480
	ds_read_b128 v[118:121], v192 offset:21504
	ds_read_b128 v[122:125], v192 offset:22528
	ds_read_b128 v[126:129], v192 offset:23552
	global_load_lds_dwordx4 v[130:131], off
	v_lshl_add_u64 v[130:131], v[218:219], 0, s[26:27]
	s_mov_b32 m0, s31
	s_addc_u32 s79, s45, 0
	s_add_i32 s35, s73, s7
	global_load_lds_dwordx4 v[130:131], off
	v_lshl_add_u64 v[130:131], s[78:79], 0, v[148:149]
	s_mov_b32 m0, s35
	s_add_i32 s74, s35, 0x2000
	global_load_lds_dwordx4 v[130:131], off
	v_lshl_add_u64 v[130:131], s[78:79], 0, v[152:153]
	s_mov_b32 m0, s74
	v_lshl_add_u64 v[220:221], s[40:41], 0, v[146:147]
	global_load_lds_dwordx4 v[130:131], off
	v_lshl_add_u64 v[130:131], v[220:221], 0, s[26:27]
	s_mov_b32 m0, s43
	v_lshl_add_u64 v[222:223], s[40:41], 0, v[150:151]
	global_load_lds_dwordx4 v[130:131], off
	v_lshl_add_u64 v[130:131], v[222:223], 0, s[26:27]
	s_mov_b32 m0, s50
	s_nop 0
	global_load_lds_dwordx4 v[130:131], off
	s_waitcnt vmcnt(8)
	s_waitcnt lgkmcnt(0)
	s_barrier
	s_setprio 1
	v_mfma_f32_16x16x32_bf16 v[130:133], v[2:5], v[62:65], 0
	v_mfma_f32_16x16x32_bf16 v[138:141], v[2:5], v[106:109], 0
	v_mfma_f32_16x16x32_bf16 v[158:161], v[2:5], v[114:117], 0
	v_mfma_f32_16x16x32_bf16 v[2:5], v[2:5], v[122:125], 0
	v_mfma_f32_16x16x32_bf16 v[130:133], v[6:9], v[102:105], v[130:133]
	v_mfma_f32_16x16x32_bf16 v[134:137], v[10:13], v[62:65], 0
	v_mfma_f32_16x16x32_bf16 v[138:141], v[6:9], v[110:113], v[138:141]
	v_mfma_f32_16x16x32_bf16 v[142:145], v[10:13], v[106:109], 0
	v_mfma_f32_16x16x32_bf16 v[158:161], v[6:9], v[118:121], v[158:161]
	v_mfma_f32_16x16x32_bf16 v[2:5], v[6:9], v[126:129], v[2:5]
	v_mfma_f32_16x16x32_bf16 v[6:9], v[10:13], v[122:125], 0
	v_mfma_f32_16x16x32_bf16 v[134:137], v[14:17], v[102:105], v[134:137]
	v_mfma_f32_16x16x32_bf16 v[142:145], v[14:17], v[110:113], v[142:145]
	v_mfma_f32_16x16x32_bf16 v[162:165], v[10:13], v[114:117], 0
	v_mfma_f32_16x16x32_bf16 v[6:9], v[14:17], v[126:129], v[6:9]
	v_mfma_f32_16x16x32_bf16 v[162:165], v[14:17], v[118:121], v[162:165]
	v_mfma_f32_16x16x32_bf16 v[10:13], v[18:21], v[62:65], 0
	v_mfma_f32_16x16x32_bf16 v[14:17], v[26:29], v[62:65], 0
	v_mfma_f32_16x16x32_bf16 v[10:13], v[22:25], v[102:105], v[10:13]
	v_mfma_f32_16x16x32_bf16 v[14:17], v[30:33], v[102:105], v[14:17]
	v_mfma_f32_16x16x32_bf16 v[62:65], v[18:21], v[106:109], 0
	v_mfma_f32_16x16x32_bf16 v[102:105], v[26:29], v[106:109], 0
	v_mfma_f32_16x16x32_bf16 v[62:65], v[22:25], v[110:113], v[62:65]
	v_mfma_f32_16x16x32_bf16 v[102:105], v[30:33], v[110:113], v[102:105]
	v_mfma_f32_16x16x32_bf16 v[106:109], v[18:21], v[114:117], 0
	v_mfma_f32_16x16x32_bf16 v[110:113], v[26:29], v[114:117], 0
	v_mfma_f32_16x16x32_bf16 v[18:21], v[18:21], v[122:125], 0
	v_mfma_f32_16x16x32_bf16 v[106:109], v[22:25], v[118:121], v[106:109]
	v_mfma_f32_16x16x32_bf16 v[110:113], v[30:33], v[118:121], v[110:113]
	v_mfma_f32_16x16x32_bf16 v[18:21], v[22:25], v[126:129], v[18:21]
	v_mfma_f32_16x16x32_bf16 v[22:25], v[26:29], v[122:125], 0
	v_mfma_f32_16x16x32_bf16 v[22:25], v[30:33], v[126:129], v[22:25]
	s_setprio 0
	s_barrier
	s_add_i32 s76, 0, 0x18000
	s_add_i32 s84, 0, 0x1c000
	v_add_u32_e32 v234, s76, v173
	v_add_u32_e32 v235, s84, v173
	ds_read_b128 v[26:29], v234
	ds_read_b128 v[30:33], v234 offset:1024
	ds_read_b128 v[114:117], v234 offset:2048
	ds_read_b128 v[118:121], v234 offset:3072
	ds_read_b128 v[122:125], v235
	ds_read_b128 v[126:129], v235 offset:1024
	ds_read_b128 v[166:169], v235 offset:2048
	ds_read_b128 v[176:179], v235 offset:3072
	s_add_u32 s78, s40, 0x40100
	s_addc_u32 s79, s41, 0
	s_mov_b32 m0, s51
	v_lshl_add_u64 v[224:225], s[78:79], 0, v[146:147]
	ds_read_b128 v[180:183], v192 offset:32768
	ds_read_b128 v[184:187], v192 offset:33792
	ds_read_b128 v[194:197], v192 offset:34816
	ds_read_b128 v[198:201], v192 offset:35840
	ds_read_b128 v[202:205], v192 offset:36864
	ds_read_b128 v[206:209], v192 offset:37888
	ds_read_b128 v[210:213], v192 offset:38912
	ds_read_b128 v[214:217], v192 offset:39936
	global_load_lds_dwordx4 v[224:225], off
	v_lshl_add_u64 v[224:225], s[78:79], 0, v[150:151]
	s_mov_b32 m0, s54
	s_nop 0
	global_load_lds_dwordx4 v[224:225], off
	s_waitcnt vmcnt(8)
	s_waitcnt lgkmcnt(0)
	s_barrier
	s_setprio 1
	v_mfma_f32_16x16x32_bf16 v[66:69], v[26:29], v[180:183], v[66:69]
	v_mfma_f32_16x16x32_bf16 v[70:73], v[114:117], v[180:183], v[70:73]
	v_mfma_f32_16x16x32_bf16 v[74:77], v[26:29], v[194:197], v[74:77]
	v_mfma_f32_16x16x32_bf16 v[78:81], v[114:117], v[194:197], v[78:81]
	v_mfma_f32_16x16x32_bf16 v[82:85], v[26:29], v[202:205], v[82:85]
	v_mfma_f32_16x16x32_bf16 v[86:89], v[114:117], v[202:205], v[86:89]
	v_mfma_f32_16x16x32_bf16 v[90:93], v[26:29], v[210:213], v[90:93]
	v_mfma_f32_16x16x32_bf16 v[94:97], v[114:117], v[210:213], v[94:97]
	v_mfma_f32_16x16x32_bf16 v[66:69], v[30:33], v[184:187], v[66:69]
	v_mfma_f32_16x16x32_bf16 v[70:73], v[118:121], v[184:187], v[70:73]
	v_mfma_f32_16x16x32_bf16 v[74:77], v[30:33], v[198:201], v[74:77]
	v_mfma_f32_16x16x32_bf16 v[78:81], v[118:121], v[198:201], v[78:81]
	v_mfma_f32_16x16x32_bf16 v[82:85], v[30:33], v[206:209], v[82:85]
	v_mfma_f32_16x16x32_bf16 v[86:89], v[118:121], v[206:209], v[86:89]
	v_mfma_f32_16x16x32_bf16 v[90:93], v[30:33], v[214:217], v[90:93]
	v_mfma_f32_16x16x32_bf16 v[94:97], v[118:121], v[214:217], v[94:97]
	v_mfma_f32_16x16x32_bf16 v[98:101], v[122:125], v[180:183], v[98:101]
	v_mfma_f32_16x16x32_bf16 v[34:37], v[166:169], v[180:183], v[34:37]
	v_mfma_f32_16x16x32_bf16 v[38:41], v[122:125], v[194:197], v[38:41]
	v_mfma_f32_16x16x32_bf16 v[42:45], v[166:169], v[194:197], v[42:45]
	v_mfma_f32_16x16x32_bf16 v[46:49], v[122:125], v[202:205], v[46:49]
	v_mfma_f32_16x16x32_bf16 v[50:53], v[166:169], v[202:205], v[50:53]
	v_mfma_f32_16x16x32_bf16 v[54:57], v[122:125], v[210:213], v[54:57]
	v_mfma_f32_16x16x32_bf16 v[58:61], v[166:169], v[210:213], v[58:61]
	v_mfma_f32_16x16x32_bf16 v[98:101], v[126:129], v[184:187], v[98:101]
	v_mfma_f32_16x16x32_bf16 v[34:37], v[176:179], v[184:187], v[34:37]
	v_mfma_f32_16x16x32_bf16 v[38:41], v[126:129], v[198:201], v[38:41]
	v_mfma_f32_16x16x32_bf16 v[42:45], v[176:179], v[198:201], v[42:45]
	v_mfma_f32_16x16x32_bf16 v[46:49], v[126:129], v[206:209], v[46:49]
	v_mfma_f32_16x16x32_bf16 v[50:53], v[176:179], v[206:209], v[50:53]
	v_mfma_f32_16x16x32_bf16 v[54:57], v[126:129], v[214:217], v[54:57]
	v_mfma_f32_16x16x32_bf16 v[58:61], v[176:179], v[214:217], v[58:61]
	s_setprio 0
	s_barrier
	s_add_i32 s78, s76, s7
	s_add_i32 s76, s78, 0x2000
	v_lshl_add_u64 v[188:189], v[188:189], 0, s[28:29]
	s_mov_b32 m0, s78
	s_add_u32 s80, s44, 0x10180
	ds_read_b128 v[180:183], v192 offset:49152
	ds_read_b128 v[184:187], v192 offset:50176
	ds_read_b128 v[194:197], v192 offset:51200
	ds_read_b128 v[198:201], v192 offset:52224
	ds_read_b128 v[202:205], v192 offset:53248
	ds_read_b128 v[206:209], v192 offset:54272
	ds_read_b128 v[210:213], v192 offset:55296
	ds_read_b128 v[214:217], v192 offset:56320
	global_load_lds_dwordx4 v[188:189], off
	v_lshl_add_u64 v[188:189], v[218:219], 0, s[28:29]
	s_mov_b32 m0, s76
	s_addc_u32 s81, s45, 0
	s_add_i32 s44, s84, s7
	global_load_lds_dwordx4 v[188:189], off
	v_lshl_add_u64 v[188:189], s[80:81], 0, v[148:149]
	s_mov_b32 m0, s44
	s_add_i32 s45, s44, 0x2000
	global_load_lds_dwordx4 v[188:189], off
	v_lshl_add_u64 v[188:189], s[80:81], 0, v[152:153]
	s_mov_b32 m0, s45
	s_nop 0
	global_load_lds_dwordx4 v[188:189], off
	v_lshl_add_u64 v[188:189], v[220:221], 0, s[28:29]
	s_mov_b32 m0, s65
	s_nop 0
	global_load_lds_dwordx4 v[188:189], off
	v_lshl_add_u64 v[188:189], v[222:223], 0, s[28:29]
	s_mov_b32 m0, s70
	s_nop 0
	global_load_lds_dwordx4 v[188:189], off
	s_waitcnt vmcnt(8)
	s_waitcnt lgkmcnt(0)
	s_barrier
	s_setprio 1
	v_mfma_f32_16x16x32_bf16 v[130:133], v[26:29], v[180:183], v[130:133]
	v_mfma_f32_16x16x32_bf16 v[134:137], v[114:117], v[180:183], v[134:137]
	v_mfma_f32_16x16x32_bf16 v[138:141], v[26:29], v[194:197], v[138:141]
	v_mfma_f32_16x16x32_bf16 v[142:145], v[114:117], v[194:197], v[142:145]
	v_mfma_f32_16x16x32_bf16 v[2:5], v[26:29], v[210:213], v[2:5]
	v_mfma_f32_16x16x32_bf16 v[6:9], v[114:117], v[210:213], v[6:9]
	v_mfma_f32_16x16x32_bf16 v[130:133], v[30:33], v[184:187], v[130:133]
	v_mfma_f32_16x16x32_bf16 v[134:137], v[118:121], v[184:187], v[134:137]
	v_mfma_f32_16x16x32_bf16 v[138:141], v[30:33], v[198:201], v[138:141]
	v_mfma_f32_16x16x32_bf16 v[142:145], v[118:121], v[198:201], v[142:145]
	v_mfma_f32_16x16x32_bf16 v[158:161], v[26:29], v[202:205], v[158:161]
	v_mfma_f32_16x16x32_bf16 v[162:165], v[114:117], v[202:205], v[162:165]
	v_mfma_f32_16x16x32_bf16 v[2:5], v[30:33], v[214:217], v[2:5]
	v_mfma_f32_16x16x32_bf16 v[6:9], v[118:121], v[214:217], v[6:9]
	v_mfma_f32_16x16x32_bf16 v[158:161], v[30:33], v[206:209], v[158:161]
	v_mfma_f32_16x16x32_bf16 v[162:165], v[118:121], v[206:209], v[162:165]
	v_mfma_f32_16x16x32_bf16 v[10:13], v[122:125], v[180:183], v[10:13]
	v_mfma_f32_16x16x32_bf16 v[14:17], v[166:169], v[180:183], v[14:17]
	v_mfma_f32_16x16x32_bf16 v[26:29], v[122:125], v[194:197], v[62:65]
	v_mfma_f32_16x16x32_bf16 v[30:33], v[166:169], v[194:197], v[102:105]
	v_mfma_f32_16x16x32_bf16 v[62:65], v[122:125], v[202:205], v[106:109]
	v_mfma_f32_16x16x32_bf16 v[102:105], v[166:169], v[202:205], v[110:113]
	v_mfma_f32_16x16x32_bf16 v[10:13], v[126:129], v[184:187], v[10:13]
	v_mfma_f32_16x16x32_bf16 v[14:17], v[176:179], v[184:187], v[14:17]
	v_mfma_f32_16x16x32_bf16 v[62:65], v[126:129], v[206:209], v[62:65]
	v_mfma_f32_16x16x32_bf16 v[102:105], v[176:179], v[206:209], v[102:105]
	v_mfma_f32_16x16x32_bf16 v[18:21], v[122:125], v[210:213], v[18:21]
	v_mfma_f32_16x16x32_bf16 v[22:25], v[166:169], v[210:213], v[22:25]
	v_mfma_f32_16x16x32_bf16 v[26:29], v[126:129], v[198:201], v[26:29]
	v_mfma_f32_16x16x32_bf16 v[30:33], v[176:179], v[198:201], v[30:33]
	v_mfma_f32_16x16x32_bf16 v[18:21], v[126:129], v[214:217], v[18:21]
	v_mfma_f32_16x16x32_bf16 v[22:25], v[176:179], v[214:217], v[22:25]
	s_setprio 0
	s_barrier
	ds_read_b128 v[106:109], v190
	ds_read_b128 v[110:113], v190 offset:1024
	ds_read_b128 v[114:117], v190 offset:2048
	ds_read_b128 v[118:121], v190 offset:3072
	ds_read_b128 v[122:125], v191
	ds_read_b128 v[126:129], v191 offset:1024
	ds_read_b128 v[166:169], v191 offset:2048
	ds_read_b128 v[176:179], v191 offset:3072
	s_add_u32 s40, s40, 0x40180
	s_addc_u32 s41, s41, 0
	s_mov_b32 m0, s77
	v_lshl_add_u64 v[188:189], s[40:41], 0, v[146:147]
	ds_read_b128 v[180:183], v192
	ds_read_b128 v[184:187], v192 offset:1024
	ds_read_b128 v[194:197], v192 offset:2048
	ds_read_b128 v[198:201], v192 offset:3072
	ds_read_b128 v[202:205], v192 offset:4096
	ds_read_b128 v[206:209], v192 offset:5120
	ds_read_b128 v[210:213], v192 offset:6144
	ds_read_b128 v[214:217], v192 offset:7168
	global_load_lds_dwordx4 v[188:189], off
	v_lshl_add_u64 v[188:189], s[40:41], 0, v[150:151]
	s_mov_b32 m0, s9
	s_nop 0
	global_load_lds_dwordx4 v[188:189], off
	s_waitcnt vmcnt(8)
	s_waitcnt lgkmcnt(0)
	s_barrier
	s_setprio 1
	v_mfma_f32_16x16x32_bf16 v[66:69], v[106:109], v[180:183], v[66:69]
	v_mfma_f32_16x16x32_bf16 v[70:73], v[114:117], v[180:183], v[70:73]
	v_mfma_f32_16x16x32_bf16 v[74:77], v[106:109], v[194:197], v[74:77]
	v_mfma_f32_16x16x32_bf16 v[78:81], v[114:117], v[194:197], v[78:81]
	v_mfma_f32_16x16x32_bf16 v[82:85], v[106:109], v[202:205], v[82:85]
	v_mfma_f32_16x16x32_bf16 v[86:89], v[114:117], v[202:205], v[86:89]
	v_mfma_f32_16x16x32_bf16 v[90:93], v[106:109], v[210:213], v[90:93]
	v_mfma_f32_16x16x32_bf16 v[94:97], v[114:117], v[210:213], v[94:97]
	v_mfma_f32_16x16x32_bf16 v[66:69], v[110:113], v[184:187], v[66:69]
	v_mfma_f32_16x16x32_bf16 v[70:73], v[118:121], v[184:187], v[70:73]
	v_mfma_f32_16x16x32_bf16 v[74:77], v[110:113], v[198:201], v[74:77]
	v_mfma_f32_16x16x32_bf16 v[78:81], v[118:121], v[198:201], v[78:81]
	v_mfma_f32_16x16x32_bf16 v[82:85], v[110:113], v[206:209], v[82:85]
	v_mfma_f32_16x16x32_bf16 v[86:89], v[118:121], v[206:209], v[86:89]
	v_mfma_f32_16x16x32_bf16 v[90:93], v[110:113], v[214:217], v[90:93]
	v_mfma_f32_16x16x32_bf16 v[94:97], v[118:121], v[214:217], v[94:97]
	v_mfma_f32_16x16x32_bf16 v[34:37], v[166:169], v[180:183], v[34:37]
	v_mfma_f32_16x16x32_bf16 v[38:41], v[122:125], v[194:197], v[38:41]
	v_mfma_f32_16x16x32_bf16 v[42:45], v[166:169], v[194:197], v[42:45]
	v_mfma_f32_16x16x32_bf16 v[46:49], v[122:125], v[202:205], v[46:49]
	v_mfma_f32_16x16x32_bf16 v[50:53], v[166:169], v[202:205], v[50:53]
	v_mfma_f32_16x16x32_bf16 v[54:57], v[122:125], v[210:213], v[54:57]
	v_mfma_f32_16x16x32_bf16 v[58:61], v[166:169], v[210:213], v[58:61]
	v_mfma_f32_16x16x32_bf16 v[98:101], v[122:125], v[180:183], v[98:101]
	v_mfma_f32_16x16x32_bf16 v[34:37], v[176:179], v[184:187], v[34:37]
	v_mfma_f32_16x16x32_bf16 v[38:41], v[126:129], v[198:201], v[38:41]
	v_mfma_f32_16x16x32_bf16 v[42:45], v[176:179], v[198:201], v[42:45]
	v_mfma_f32_16x16x32_bf16 v[46:49], v[126:129], v[206:209], v[46:49]
	v_mfma_f32_16x16x32_bf16 v[50:53], v[176:179], v[206:209], v[50:53]
	v_mfma_f32_16x16x32_bf16 v[54:57], v[126:129], v[214:217], v[54:57]
	v_mfma_f32_16x16x32_bf16 v[58:61], v[176:179], v[214:217], v[58:61]
	v_mfma_f32_16x16x32_bf16 v[218:221], v[126:129], v[184:187], v[98:101]
	s_setprio 0
	s_barrier
	s_mov_b32 m0, s75
	v_lshl_add_u64 v[188:189], s[46:47], 0, v[148:149]
	s_add_u32 s40, s46, 0x10000
	ds_read_b128 v[98:101], v192 offset:16384
	ds_read_b128 v[180:183], v192 offset:17408
	ds_read_b128 v[184:187], v192 offset:18432
	ds_read_b128 v[194:197], v192 offset:19456
	ds_read_b128 v[198:201], v192 offset:20480
	ds_read_b128 v[202:205], v192 offset:21504
	ds_read_b128 v[206:209], v192 offset:22528
	ds_read_b128 v[210:213], v192 offset:23552
	global_load_lds_dwordx4 v[188:189], off
	v_lshl_add_u64 v[154:155], s[46:47], 0, v[152:153]
	s_mov_b32 m0, s31
	s_addc_u32 s41, s47, 0
	global_load_lds_dwordx4 v[154:155], off
	v_lshl_add_u64 v[214:215], s[40:41], 0, v[148:149]
	s_mov_b32 m0, s35
	v_lshl_add_u64 v[0:1], s[48:49], 0, v[146:147]
	global_load_lds_dwordx4 v[214:215], off
	v_lshl_add_u64 v[214:215], s[40:41], 0, v[152:153]
	s_mov_b32 m0, s74
	v_lshl_add_u64 v[156:157], s[48:49], 0, v[150:151]
	global_load_lds_dwordx4 v[214:215], off
	s_mov_b32 m0, s43
	s_nop 0
	global_load_lds_dwordx4 v[0:1], off
	s_mov_b32 m0, s50
	s_nop 0
	global_load_lds_dwordx4 v[156:157], off
	s_waitcnt vmcnt(8)
	s_waitcnt lgkmcnt(0)
	s_barrier
	s_setprio 1
	v_mfma_f32_16x16x32_bf16 v[130:133], v[106:109], v[98:101], v[130:133]
	v_mfma_f32_16x16x32_bf16 v[214:217], v[110:113], v[180:183], v[130:133]
	v_mfma_f32_16x16x32_bf16 v[130:133], v[114:117], v[98:101], v[134:137]
	v_mfma_f32_16x16x32_bf16 v[222:225], v[118:121], v[180:183], v[130:133]
	v_mfma_f32_16x16x32_bf16 v[130:133], v[106:109], v[184:187], v[138:141]
	v_mfma_f32_16x16x32_bf16 v[226:229], v[110:113], v[194:197], v[130:133]
	v_mfma_f32_16x16x32_bf16 v[130:133], v[114:117], v[184:187], v[142:145]
	v_mfma_f32_16x16x32_bf16 v[230:233], v[118:121], v[194:197], v[130:133]
	v_mfma_f32_16x16x32_bf16 v[130:133], v[106:109], v[198:201], v[158:161]
	v_mfma_f32_16x16x32_bf16 v[2:5], v[106:109], v[206:209], v[2:5]
	v_mfma_f32_16x16x32_bf16 v[6:9], v[114:117], v[206:209], v[6:9]
	v_mfma_f32_16x16x32_bf16 v[158:161], v[110:113], v[202:205], v[130:133]
	v_mfma_f32_16x16x32_bf16 v[130:133], v[114:117], v[198:201], v[162:165]
	v_mfma_f32_16x16x32_bf16 v[2:5], v[110:113], v[210:213], v[2:5]
	v_mfma_f32_16x16x32_bf16 v[6:9], v[118:121], v[210:213], v[6:9]
	v_mfma_f32_16x16x32_bf16 v[162:165], v[118:121], v[202:205], v[130:133]
	v_mfma_f32_16x16x32_bf16 v[10:13], v[122:125], v[98:101], v[10:13]
	v_mfma_f32_16x16x32_bf16 v[14:17], v[166:169], v[98:101], v[14:17]
	v_mfma_f32_16x16x32_bf16 v[62:65], v[122:125], v[198:201], v[62:65]
	v_mfma_f32_16x16x32_bf16 v[10:13], v[126:129], v[180:183], v[10:13]
	v_mfma_f32_16x16x32_bf16 v[14:17], v[176:179], v[180:183], v[14:17]
	v_mfma_f32_16x16x32_bf16 v[26:29], v[122:125], v[184:187], v[26:29]
	v_mfma_f32_16x16x32_bf16 v[30:33], v[166:169], v[184:187], v[30:33]
	v_mfma_f32_16x16x32_bf16 v[180:183], v[126:129], v[202:205], v[62:65]
	v_mfma_f32_16x16x32_bf16 v[62:65], v[166:169], v[198:201], v[102:105]
	v_mfma_f32_16x16x32_bf16 v[18:21], v[122:125], v[206:209], v[18:21]
	v_mfma_f32_16x16x32_bf16 v[22:25], v[166:169], v[206:209], v[22:25]
	v_mfma_f32_16x16x32_bf16 v[26:29], v[126:129], v[194:197], v[26:29]
	v_mfma_f32_16x16x32_bf16 v[30:33], v[176:179], v[194:197], v[30:33]
	v_mfma_f32_16x16x32_bf16 v[184:187], v[176:179], v[202:205], v[62:65]
	v_mfma_f32_16x16x32_bf16 v[18:21], v[126:129], v[210:213], v[18:21]
	v_mfma_f32_16x16x32_bf16 v[22:25], v[176:179], v[210:213], v[22:25]
	s_setprio 0
	s_barrier
	ds_read_b128 v[62:65], v234
	ds_read_b128 v[166:169], v234 offset:1024
	ds_read_b128 v[176:179], v234 offset:2048
	ds_read_b128 v[194:197], v234 offset:3072
	ds_read_b128 v[198:201], v235
	ds_read_b128 v[202:205], v235 offset:1024
	ds_read_b128 v[206:209], v235 offset:2048
	ds_read_b128 v[210:213], v235 offset:3072
	s_add_u32 s40, s48, 0x40000
	s_addc_u32 s41, s49, 0
	s_mov_b32 m0, s51
	v_lshl_add_u64 v[98:99], s[40:41], 0, v[146:147]
	ds_read_b128 v[106:109], v192 offset:32768
	ds_read_b128 v[110:113], v192 offset:33792
	ds_read_b128 v[126:129], v192 offset:34816
	ds_read_b128 v[234:237], v192 offset:35840
	ds_read_b128 v[238:241], v192 offset:36864
	ds_read_b128 v[242:245], v192 offset:37888
	ds_read_b128 v[246:249], v192 offset:38912
	ds_read_b128 v[250:253], v192 offset:39936
	global_load_lds_dwordx4 v[98:99], off
	v_lshl_add_u64 v[98:99], s[40:41], 0, v[150:151]
	s_mov_b32 m0, s54
	s_nop 0
	global_load_lds_dwordx4 v[98:99], off
	s_waitcnt vmcnt(8)
	s_waitcnt lgkmcnt(0)
	s_barrier
	s_setprio 1
	v_mfma_f32_16x16x32_bf16 v[66:69], v[62:65], v[106:109], v[66:69]
	v_mfma_f32_16x16x32_bf16 v[130:133], v[166:169], v[110:113], v[66:69]
	v_mfma_f32_16x16x32_bf16 v[66:69], v[176:179], v[106:109], v[70:73]
	v_mfma_f32_16x16x32_bf16 v[134:137], v[194:197], v[110:113], v[66:69]
	v_mfma_f32_16x16x32_bf16 v[66:69], v[62:65], v[126:129], v[74:77]
	v_mfma_f32_16x16x32_bf16 v[114:117], v[166:169], v[234:237], v[66:69]
	v_mfma_f32_16x16x32_bf16 v[66:69], v[176:179], v[126:129], v[78:81]
	v_mfma_f32_16x16x32_bf16 v[118:121], v[194:197], v[234:237], v[66:69]
	v_mfma_f32_16x16x32_bf16 v[66:69], v[62:65], v[238:241], v[82:85]
	v_mfma_f32_16x16x32_bf16 v[98:101], v[166:169], v[242:245], v[66:69]
	v_mfma_f32_16x16x32_bf16 v[66:69], v[176:179], v[238:241], v[86:89]
	v_mfma_f32_16x16x32_bf16 v[102:105], v[194:197], v[242:245], v[66:69]
	v_mfma_f32_16x16x32_bf16 v[66:69], v[62:65], v[246:249], v[90:93]
	v_mfma_f32_16x16x32_bf16 v[82:85], v[166:169], v[250:253], v[66:69]
	v_mfma_f32_16x16x32_bf16 v[66:69], v[176:179], v[246:249], v[94:97]
	v_mfma_f32_16x16x32_bf16 v[86:89], v[194:197], v[250:253], v[66:69]
	v_mfma_f32_16x16x32_bf16 v[34:37], v[206:209], v[106:109], v[34:37]
	v_mfma_f32_16x16x32_bf16 v[142:145], v[210:213], v[110:113], v[34:37]
	v_mfma_f32_16x16x32_bf16 v[34:37], v[198:201], v[126:129], v[38:41]
	v_mfma_f32_16x16x32_bf16 v[122:125], v[202:205], v[234:237], v[34:37]
	v_mfma_f32_16x16x32_bf16 v[34:37], v[206:209], v[126:129], v[42:45]
	v_mfma_f32_16x16x32_bf16 v[126:129], v[210:213], v[234:237], v[34:37]
	v_mfma_f32_16x16x32_bf16 v[34:37], v[198:201], v[238:241], v[46:49]
	v_mfma_f32_16x16x32_bf16 v[66:69], v[198:201], v[106:109], v[218:221]
	v_mfma_f32_16x16x32_bf16 v[106:109], v[202:205], v[242:245], v[34:37]
	v_mfma_f32_16x16x32_bf16 v[34:37], v[206:209], v[238:241], v[50:53]
	v_mfma_f32_16x16x32_bf16 v[138:141], v[202:205], v[110:113], v[66:69]
	v_mfma_f32_16x16x32_bf16 v[110:113], v[210:213], v[242:245], v[34:37]
	v_mfma_f32_16x16x32_bf16 v[34:37], v[198:201], v[246:249], v[54:57]
	v_mfma_f32_16x16x32_bf16 v[90:93], v[202:205], v[250:253], v[34:37]
	v_mfma_f32_16x16x32_bf16 v[34:37], v[206:209], v[246:249], v[58:61]
	v_mfma_f32_16x16x32_bf16 v[94:97], v[210:213], v[250:253], v[34:37]
	s_setprio 0
	s_barrier
	s_mov_b32 m0, s78
	s_nop 3
	v_lshl_add_u64 v[34:35], v[188:189], 0, s[18:19]
	s_add_u32 s40, s46, 0x10080
	ds_read_b128 v[42:45], v192 offset:49152
	ds_read_b128 v[46:49], v192 offset:50176
	ds_read_b128 v[218:221], v192 offset:51200
	ds_read_b128 v[234:237], v192 offset:52224
	ds_read_b128 v[238:241], v192 offset:53248
	ds_read_b128 v[242:245], v192 offset:54272
	ds_read_b128 v[246:249], v192 offset:55296
	ds_read_b128 v[250:253], v192 offset:56320
	global_load_lds_dwordx4 v[34:35], off
	v_lshl_add_u64 v[34:35], v[154:155], 0, s[18:19]
	s_mov_b32 m0, s76
	s_addc_u32 s41, s47, 0
	global_load_lds_dwordx4 v[34:35], off
	v_lshl_add_u64 v[34:35], s[40:41], 0, v[148:149]
	s_mov_b32 m0, s44
	v_lshl_add_u64 v[0:1], v[0:1], 0, s[18:19]
	global_load_lds_dwordx4 v[34:35], off
	v_lshl_add_u64 v[34:35], s[40:41], 0, v[152:153]
	s_mov_b32 m0, s45
	s_nop 0
	global_load_lds_dwordx4 v[34:35], off
	s_mov_b32 m0, s65
	s_nop 0
	global_load_lds_dwordx4 v[0:1], off
	v_lshl_add_u64 v[0:1], v[156:157], 0, s[18:19]
	s_mov_b32 m0, s70
	s_nop 0
	global_load_lds_dwordx4 v[0:1], off
	s_waitcnt vmcnt(8)
	s_waitcnt lgkmcnt(0)
	s_barrier
	s_setprio 1
	v_mfma_f32_16x16x32_bf16 v[34:37], v[62:65], v[42:45], v[214:217]
	v_mfma_f32_16x16x32_bf16 v[66:69], v[166:169], v[46:49], v[34:37]
	v_mfma_f32_16x16x32_bf16 v[34:37], v[176:179], v[42:45], v[222:225]
	v_mfma_f32_16x16x32_bf16 v[70:73], v[194:197], v[46:49], v[34:37]
	v_mfma_f32_16x16x32_bf16 v[34:37], v[62:65], v[218:221], v[226:229]
	v_mfma_f32_16x16x32_bf16 v[50:53], v[166:169], v[234:237], v[34:37]
	v_mfma_f32_16x16x32_bf16 v[34:37], v[176:179], v[218:221], v[230:233]
	v_mfma_f32_16x16x32_bf16 v[54:57], v[194:197], v[234:237], v[34:37]
	v_mfma_f32_16x16x32_bf16 v[34:37], v[62:65], v[238:241], v[158:161]
	v_mfma_f32_16x16x32_bf16 v[38:41], v[176:179], v[238:241], v[162:165]
	v_mfma_f32_16x16x32_bf16 v[2:5], v[62:65], v[246:249], v[2:5]
	v_mfma_f32_16x16x32_bf16 v[6:9], v[176:179], v[246:249], v[6:9]
	v_mfma_f32_16x16x32_bf16 v[34:37], v[166:169], v[242:245], v[34:37]
	v_mfma_f32_16x16x32_bf16 v[38:41], v[194:197], v[242:245], v[38:41]
	v_mfma_f32_16x16x32_bf16 v[2:5], v[166:169], v[250:253], v[2:5]
	v_mfma_f32_16x16x32_bf16 v[6:9], v[194:197], v[250:253], v[6:9]
	v_mfma_f32_16x16x32_bf16 v[10:13], v[198:201], v[42:45], v[10:13]
	v_mfma_f32_16x16x32_bf16 v[74:77], v[202:205], v[46:49], v[10:13]
	v_mfma_f32_16x16x32_bf16 v[10:13], v[206:209], v[42:45], v[14:17]
	v_mfma_f32_16x16x32_bf16 v[78:81], v[210:213], v[46:49], v[10:13]
	v_mfma_f32_16x16x32_bf16 v[10:13], v[198:201], v[218:221], v[26:29]
	v_mfma_f32_16x16x32_bf16 v[58:61], v[202:205], v[234:237], v[10:13]
	v_mfma_f32_16x16x32_bf16 v[10:13], v[206:209], v[218:221], v[30:33]
	v_mfma_f32_16x16x32_bf16 v[62:65], v[210:213], v[234:237], v[10:13]
	v_mfma_f32_16x16x32_bf16 v[10:13], v[198:201], v[238:241], v[180:183]
	v_mfma_f32_16x16x32_bf16 v[42:45], v[202:205], v[242:245], v[10:13]
	v_mfma_f32_16x16x32_bf16 v[10:13], v[206:209], v[238:241], v[184:187]
	v_mfma_f32_16x16x32_bf16 v[46:49], v[210:213], v[242:245], v[10:13]
	v_mfma_f32_16x16x32_bf16 v[10:13], v[198:201], v[246:249], v[18:21]
	v_mfma_f32_16x16x32_bf16 v[14:17], v[206:209], v[246:249], v[22:25]
	v_mfma_f32_16x16x32_bf16 v[10:13], v[202:205], v[250:253], v[10:13]
	v_mfma_f32_16x16x32_bf16 v[14:17], v[210:213], v[250:253], v[14:17]
	s_setprio 0
	s_barrier
	s_andn2_b64 vcc, exec, s[20:21]
	s_cbranch_vccnz .LBB0_1205
	s_barrier

.LBB0_1317:
	ds_read_b128 v[30:33], v219
	ds_read_b128 v[54:57], v219 offset:1024
	ds_read_b128 v[118:121], v219 offset:2048
	ds_read_b128 v[122:125], v219 offset:3072
	ds_read_b128 v[146:149], v220
	ds_read_b128 v[150:153], v220 offset:1024
	ds_read_b128 v[154:157], v220 offset:2048
	ds_read_b128 v[158:161], v220 offset:3072
	s_add_u32 s52, s8, 0xfffc0080
	s_addc_u32 s53, s9, -1
	s_cmp_eq_u32 s93, 12
	s_cselect_b32 s55, s45, s53
	s_cselect_b32 s54, s51, s52
	s_cselect_b32 s53, s43, s92
	s_cselect_b32 s52, s90, s91
	v_lshl_add_u64 v[232:233], s[8:9], 0, v[188:189]
	s_add_i32 m0, s59, 0xc000
	ds_read_b128 v[162:165], v221
	ds_read_b128 v[166:169], v221 offset:1024
	ds_read_b128 v[196:199], v221 offset:2048
	ds_read_b128 v[200:203], v221 offset:3072
	ds_read_b128 v[204:207], v221 offset:4096
	ds_read_b128 v[208:211], v221 offset:5120
	ds_read_b128 v[224:227], v221 offset:6144
	ds_read_b128 v[228:231], v221 offset:7168
	global_load_lds_dwordx4 v[232:233], off
	v_lshl_add_u64 v[232:233], s[8:9], 0, v[190:191]
	s_add_i32 m0, s59, 0xe000
	s_nop 0
	global_load_lds_dwordx4 v[232:233], off
	s_waitcnt vmcnt(8)
	s_waitcnt lgkmcnt(0)
	s_barrier
	s_setprio 1
	v_mfma_f32_16x16x32_bf16 v[62:65], v[30:33], v[162:165], v[62:65]
	v_mfma_f32_16x16x32_bf16 v[42:45], v[118:121], v[162:165], v[42:45]
	v_mfma_f32_16x16x32_bf16 v[50:53], v[30:33], v[196:199], v[50:53]
	v_mfma_f32_16x16x32_bf16 v[38:41], v[118:121], v[196:199], v[38:41]
	v_mfma_f32_16x16x32_bf16 v[46:49], v[30:33], v[204:207], v[46:49]
	v_mfma_f32_16x16x32_bf16 v[34:37], v[118:121], v[204:207], v[34:37]
	v_mfma_f32_16x16x32_bf16 v[142:145], v[30:33], v[224:227], v[142:145]
	v_mfma_f32_16x16x32_bf16 v[82:85], v[118:121], v[224:227], v[82:85]
	v_mfma_f32_16x16x32_bf16 v[62:65], v[54:57], v[166:169], v[62:65]
	v_mfma_f32_16x16x32_bf16 v[42:45], v[122:125], v[166:169], v[42:45]
	v_mfma_f32_16x16x32_bf16 v[50:53], v[54:57], v[200:203], v[50:53]
	v_mfma_f32_16x16x32_bf16 v[38:41], v[122:125], v[200:203], v[38:41]
	v_mfma_f32_16x16x32_bf16 v[46:49], v[54:57], v[208:211], v[46:49]
	v_mfma_f32_16x16x32_bf16 v[34:37], v[122:125], v[208:211], v[34:37]
	v_mfma_f32_16x16x32_bf16 v[142:145], v[54:57], v[228:231], v[142:145]
	v_mfma_f32_16x16x32_bf16 v[82:85], v[122:125], v[228:231], v[82:85]
	v_mfma_f32_16x16x32_bf16 v[134:137], v[146:149], v[162:165], v[134:137]
	v_mfma_f32_16x16x32_bf16 v[74:77], v[154:157], v[162:165], v[74:77]
	v_mfma_f32_16x16x32_bf16 v[130:133], v[146:149], v[196:199], v[130:133]
	v_mfma_f32_16x16x32_bf16 v[70:73], v[154:157], v[196:199], v[70:73]
	v_mfma_f32_16x16x32_bf16 v[78:81], v[146:149], v[204:207], v[78:81]
	v_mfma_f32_16x16x32_bf16 v[66:69], v[154:157], v[204:207], v[66:69]
	v_mfma_f32_16x16x32_bf16 v[138:141], v[146:149], v[224:227], v[138:141]
	v_mfma_f32_16x16x32_bf16 v[98:101], v[154:157], v[224:227], v[98:101]
	v_mfma_f32_16x16x32_bf16 v[134:137], v[150:153], v[166:169], v[134:137]
	v_mfma_f32_16x16x32_bf16 v[74:77], v[158:161], v[166:169], v[74:77]
	v_mfma_f32_16x16x32_bf16 v[130:133], v[150:153], v[200:203], v[130:133]
	v_mfma_f32_16x16x32_bf16 v[70:73], v[158:161], v[200:203], v[70:73]
	v_mfma_f32_16x16x32_bf16 v[78:81], v[150:153], v[208:211], v[78:81]
	v_mfma_f32_16x16x32_bf16 v[66:69], v[158:161], v[208:211], v[66:69]
	v_mfma_f32_16x16x32_bf16 v[138:141], v[150:153], v[228:231], v[138:141]
	v_mfma_f32_16x16x32_bf16 v[98:101], v[158:161], v[228:231], v[98:101]
	s_setprio 0
	s_barrier
	s_add_i32 s84, s75, s57
	v_lshl_add_u64 v[232:233], s[52:53], 0, v[178:179]
	s_mov_b32 m0, s84
	ds_read_b128 v[162:165], v221 offset:16384
	ds_read_b128 v[166:169], v221 offset:17408
	ds_read_b128 v[196:199], v221 offset:18432
	ds_read_b128 v[200:203], v221 offset:19456
	ds_read_b128 v[204:207], v221 offset:20480
	ds_read_b128 v[208:211], v221 offset:21504
	ds_read_b128 v[224:227], v221 offset:22528
	ds_read_b128 v[228:231], v221 offset:23552
	global_load_lds_dwordx4 v[232:233], off
	s_add_i32 m0, s84, 0x2000
	s_add_u32 s84, s52, 0x40000
	v_lshl_add_u64 v[234:235], s[52:53], 0, v[182:183]
	s_addc_u32 s85, s53, 0
	s_add_i32 s86, s76, s57
	global_load_lds_dwordx4 v[234:235], off
	v_lshl_add_u64 v[236:237], s[84:85], 0, v[178:179]
	s_mov_b32 m0, s86
	v_lshl_add_u64 v[238:239], s[54:55], 0, v[180:181]
	global_load_lds_dwordx4 v[236:237], off
	v_lshl_add_u64 v[236:237], s[84:85], 0, v[182:183]
	s_add_i32 m0, s86, 0x2000
	s_nop 0
	global_load_lds_dwordx4 v[236:237], off
	v_lshl_add_u64 v[236:237], s[54:55], 0, v[176:177]
	s_mov_b32 m0, s59
	s_nop 0
	global_load_lds_dwordx4 v[236:237], off
	s_mov_b32 m0, s62
	s_nop 0
	global_load_lds_dwordx4 v[238:239], off
	s_waitcnt vmcnt(8)
	s_waitcnt lgkmcnt(0)
	s_barrier
	s_setprio 1
	v_mfma_f32_16x16x32_bf16 v[94:97], v[30:33], v[162:165], v[94:97]
	v_mfma_f32_16x16x32_bf16 v[10:13], v[118:121], v[162:165], v[10:13]
	v_mfma_f32_16x16x32_bf16 v[90:93], v[30:33], v[196:199], v[90:93]
	v_mfma_f32_16x16x32_bf16 v[6:9], v[118:121], v[196:199], v[6:9]
	v_mfma_f32_16x16x32_bf16 v[86:89], v[30:33], v[204:207], v[86:89]
	v_mfma_f32_16x16x32_bf16 v[2:5], v[118:121], v[204:207], v[2:5]
	v_mfma_f32_16x16x32_bf16 v[26:29], v[118:121], v[224:227], v[26:29]
	v_mfma_f32_16x16x32_bf16 v[94:97], v[54:57], v[166:169], v[94:97]
	v_mfma_f32_16x16x32_bf16 v[10:13], v[122:125], v[166:169], v[10:13]
	v_mfma_f32_16x16x32_bf16 v[90:93], v[54:57], v[200:203], v[90:93]
	v_mfma_f32_16x16x32_bf16 v[6:9], v[122:125], v[200:203], v[6:9]
	v_mfma_f32_16x16x32_bf16 v[86:89], v[54:57], v[208:211], v[86:89]
	v_mfma_f32_16x16x32_bf16 v[2:5], v[122:125], v[208:211], v[2:5]
	v_mfma_f32_16x16x32_bf16 v[30:33], v[30:33], v[224:227], v[114:117]
	v_mfma_f32_16x16x32_bf16 v[26:29], v[122:125], v[228:231], v[26:29]
	v_mfma_f32_16x16x32_bf16 v[30:33], v[54:57], v[228:231], v[30:33]
	v_mfma_f32_16x16x32_bf16 v[22:25], v[154:157], v[162:165], v[22:25]
	v_mfma_f32_16x16x32_bf16 v[106:109], v[146:149], v[196:199], v[106:109]
	v_mfma_f32_16x16x32_bf16 v[18:21], v[154:157], v[196:199], v[18:21]
	v_mfma_f32_16x16x32_bf16 v[102:105], v[146:149], v[204:207], v[102:105]
	v_mfma_f32_16x16x32_bf16 v[14:17], v[154:157], v[204:207], v[14:17]
	v_mfma_f32_16x16x32_bf16 v[58:61], v[154:157], v[224:227], v[58:61]
	v_mfma_f32_16x16x32_bf16 v[54:57], v[146:149], v[162:165], v[110:113]
	v_mfma_f32_16x16x32_bf16 v[22:25], v[158:161], v[166:169], v[22:25]
	v_mfma_f32_16x16x32_bf16 v[106:109], v[150:153], v[200:203], v[106:109]
	v_mfma_f32_16x16x32_bf16 v[18:21], v[158:161], v[200:203], v[18:21]
	v_mfma_f32_16x16x32_bf16 v[102:105], v[150:153], v[208:211], v[102:105]
	v_mfma_f32_16x16x32_bf16 v[14:17], v[158:161], v[208:211], v[14:17]
	v_mfma_f32_16x16x32_bf16 v[110:113], v[146:149], v[224:227], v[126:129]
	v_mfma_f32_16x16x32_bf16 v[58:61], v[158:161], v[228:231], v[58:61]
	v_mfma_f32_16x16x32_bf16 v[54:57], v[150:153], v[166:169], v[54:57]
	v_mfma_f32_16x16x32_bf16 v[118:121], v[150:153], v[228:231], v[110:113]
	s_setprio 0
	s_barrier
	s_add_i32 s84, 0, 0x18000
	s_add_i32 s85, 0, 0x1c000
	v_add_u32_e32 v126, s84, v175
	v_add_u32_e32 v158, s85, v175
	ds_read_b128 v[110:113], v126
	ds_read_b128 v[114:117], v126 offset:1024
	ds_read_b128 v[122:125], v126 offset:2048
	ds_read_b128 v[126:129], v126 offset:3072
	ds_read_b128 v[146:149], v158
	ds_read_b128 v[150:153], v158 offset:1024
	ds_read_b128 v[154:157], v158 offset:2048
	ds_read_b128 v[158:161], v158 offset:3072
	s_add_u32 s54, s54, 0x40000
	s_addc_u32 s55, s55, 0
	s_mov_b32 m0, s63
	v_lshl_add_u64 v[240:241], s[54:55], 0, v[176:177]
	ds_read_b128 v[162:165], v221 offset:32768
	ds_read_b128 v[166:169], v221 offset:33792
	ds_read_b128 v[196:199], v221 offset:34816
	ds_read_b128 v[200:203], v221 offset:35840
	ds_read_b128 v[204:207], v221 offset:36864
	ds_read_b128 v[208:211], v221 offset:37888
	ds_read_b128 v[224:227], v221 offset:38912
	ds_read_b128 v[228:231], v221 offset:39936
	global_load_lds_dwordx4 v[240:241], off
	v_lshl_add_u64 v[240:241], s[54:55], 0, v[180:181]
	s_mov_b32 m0, s64
	s_nop 0
	global_load_lds_dwordx4 v[240:241], off
	s_waitcnt vmcnt(8)
	s_waitcnt lgkmcnt(0)
	s_barrier
	s_setprio 1
	v_mfma_f32_16x16x32_bf16 v[62:65], v[110:113], v[162:165], v[62:65]
	v_mfma_f32_16x16x32_bf16 v[42:45], v[122:125], v[162:165], v[42:45]
	v_mfma_f32_16x16x32_bf16 v[50:53], v[110:113], v[196:199], v[50:53]
	v_mfma_f32_16x16x32_bf16 v[38:41], v[122:125], v[196:199], v[38:41]
	v_mfma_f32_16x16x32_bf16 v[46:49], v[110:113], v[204:207], v[46:49]
	v_mfma_f32_16x16x32_bf16 v[34:37], v[122:125], v[204:207], v[34:37]
	v_mfma_f32_16x16x32_bf16 v[142:145], v[110:113], v[224:227], v[142:145]
	v_mfma_f32_16x16x32_bf16 v[82:85], v[122:125], v[224:227], v[82:85]
	v_mfma_f32_16x16x32_bf16 v[62:65], v[114:117], v[166:169], v[62:65]
	v_mfma_f32_16x16x32_bf16 v[42:45], v[126:129], v[166:169], v[42:45]
	v_mfma_f32_16x16x32_bf16 v[50:53], v[114:117], v[200:203], v[50:53]
	v_mfma_f32_16x16x32_bf16 v[38:41], v[126:129], v[200:203], v[38:41]
	v_mfma_f32_16x16x32_bf16 v[46:49], v[114:117], v[208:211], v[46:49]
	v_mfma_f32_16x16x32_bf16 v[34:37], v[126:129], v[208:211], v[34:37]
	v_mfma_f32_16x16x32_bf16 v[142:145], v[114:117], v[228:231], v[142:145]
	v_mfma_f32_16x16x32_bf16 v[82:85], v[126:129], v[228:231], v[82:85]
	v_mfma_f32_16x16x32_bf16 v[134:137], v[146:149], v[162:165], v[134:137]
	v_mfma_f32_16x16x32_bf16 v[74:77], v[154:157], v[162:165], v[74:77]
	v_mfma_f32_16x16x32_bf16 v[130:133], v[146:149], v[196:199], v[130:133]
	v_mfma_f32_16x16x32_bf16 v[70:73], v[154:157], v[196:199], v[70:73]
	v_mfma_f32_16x16x32_bf16 v[78:81], v[146:149], v[204:207], v[78:81]
	v_mfma_f32_16x16x32_bf16 v[66:69], v[154:157], v[204:207], v[66:69]
	v_mfma_f32_16x16x32_bf16 v[138:141], v[146:149], v[224:227], v[138:141]
	v_mfma_f32_16x16x32_bf16 v[98:101], v[154:157], v[224:227], v[98:101]
	v_mfma_f32_16x16x32_bf16 v[134:137], v[150:153], v[166:169], v[134:137]
	v_mfma_f32_16x16x32_bf16 v[74:77], v[158:161], v[166:169], v[74:77]
	v_mfma_f32_16x16x32_bf16 v[130:133], v[150:153], v[200:203], v[130:133]
	v_mfma_f32_16x16x32_bf16 v[70:73], v[158:161], v[200:203], v[70:73]
	v_mfma_f32_16x16x32_bf16 v[78:81], v[150:153], v[208:211], v[78:81]
	v_mfma_f32_16x16x32_bf16 v[66:69], v[158:161], v[208:211], v[66:69]
	v_mfma_f32_16x16x32_bf16 v[138:141], v[150:153], v[228:231], v[138:141]
	v_mfma_f32_16x16x32_bf16 v[98:101], v[158:161], v[228:231], v[98:101]
	s_setprio 0
	s_barrier
	s_add_i32 s54, s84, s57
	v_lshl_add_u64 v[232:233], v[232:233], 0, s[34:35]
	s_mov_b32 m0, s54
	ds_read_b128 v[162:165], v221 offset:49152
	ds_read_b128 v[166:169], v221 offset:50176
	ds_read_b128 v[196:199], v221 offset:51200
	ds_read_b128 v[200:203], v221 offset:52224
	ds_read_b128 v[204:207], v221 offset:53248
	ds_read_b128 v[208:211], v221 offset:54272
	ds_read_b128 v[224:227], v221 offset:55296
	ds_read_b128 v[228:231], v221 offset:56320
	global_load_lds_dwordx4 v[232:233], off
	s_add_i32 m0, s54, 0x2000
	s_add_u32 s52, s52, 0x40080
	v_lshl_add_u64 v[232:233], v[234:235], 0, s[34:35]
	s_addc_u32 s53, s53, 0
	s_add_i32 s54, s85, s57
	global_load_lds_dwordx4 v[232:233], off
	v_lshl_add_u64 v[232:233], s[52:53], 0, v[178:179]
	s_mov_b32 m0, s54
	s_nop 0
	global_load_lds_dwordx4 v[232:233], off
	v_lshl_add_u64 v[232:233], s[52:53], 0, v[182:183]
	s_add_i32 m0, s54, 0x2000
	s_nop 0
	global_load_lds_dwordx4 v[232:233], off
	v_lshl_add_u64 v[232:233], v[236:237], 0, s[34:35]
	s_mov_b32 m0, s70
	s_nop 0
	global_load_lds_dwordx4 v[232:233], off
	v_lshl_add_u64 v[232:233], v[238:239], 0, s[34:35]
	s_mov_b32 m0, s71
	s_nop 0
	global_load_lds_dwordx4 v[232:233], off
	s_waitcnt vmcnt(8)
	s_waitcnt lgkmcnt(0)
	s_barrier
	s_setprio 1
	v_mfma_f32_16x16x32_bf16 v[94:97], v[110:113], v[162:165], v[94:97]
	v_mfma_f32_16x16x32_bf16 v[10:13], v[122:125], v[162:165], v[10:13]
	v_mfma_f32_16x16x32_bf16 v[90:93], v[110:113], v[196:199], v[90:93]
	v_mfma_f32_16x16x32_bf16 v[6:9], v[122:125], v[196:199], v[6:9]
	v_mfma_f32_16x16x32_bf16 v[86:89], v[110:113], v[204:207], v[86:89]
	v_mfma_f32_16x16x32_bf16 v[2:5], v[122:125], v[204:207], v[2:5]
	v_mfma_f32_16x16x32_bf16 v[30:33], v[110:113], v[224:227], v[30:33]
	v_mfma_f32_16x16x32_bf16 v[26:29], v[122:125], v[224:227], v[26:29]
	v_mfma_f32_16x16x32_bf16 v[94:97], v[114:117], v[166:169], v[94:97]
	v_mfma_f32_16x16x32_bf16 v[10:13], v[126:129], v[166:169], v[10:13]
	v_mfma_f32_16x16x32_bf16 v[90:93], v[114:117], v[200:203], v[90:93]
	v_mfma_f32_16x16x32_bf16 v[6:9], v[126:129], v[200:203], v[6:9]
	v_mfma_f32_16x16x32_bf16 v[86:89], v[114:117], v[208:211], v[86:89]
	v_mfma_f32_16x16x32_bf16 v[2:5], v[126:129], v[208:211], v[2:5]
	v_mfma_f32_16x16x32_bf16 v[114:117], v[114:117], v[228:231], v[30:33]
	v_mfma_f32_16x16x32_bf16 v[26:29], v[126:129], v[228:231], v[26:29]
	v_mfma_f32_16x16x32_bf16 v[30:33], v[146:149], v[162:165], v[54:57]
	v_mfma_f32_16x16x32_bf16 v[110:113], v[150:153], v[166:169], v[30:33]
	v_mfma_f32_16x16x32_bf16 v[30:33], v[146:149], v[196:199], v[106:109]
	v_mfma_f32_16x16x32_bf16 v[106:109], v[150:153], v[200:203], v[30:33]
	v_mfma_f32_16x16x32_bf16 v[30:33], v[146:149], v[204:207], v[102:105]
	v_mfma_f32_16x16x32_bf16 v[102:105], v[150:153], v[208:211], v[30:33]
	v_mfma_f32_16x16x32_bf16 v[30:33], v[146:149], v[224:227], v[118:121]
	v_mfma_f32_16x16x32_bf16 v[22:25], v[154:157], v[162:165], v[22:25]
	v_mfma_f32_16x16x32_bf16 v[18:21], v[154:157], v[196:199], v[18:21]
	v_mfma_f32_16x16x32_bf16 v[14:17], v[154:157], v[204:207], v[14:17]
	v_mfma_f32_16x16x32_bf16 v[126:129], v[150:153], v[228:231], v[30:33]
	v_mfma_f32_16x16x32_bf16 v[30:33], v[154:157], v[224:227], v[58:61]
	v_mfma_f32_16x16x32_bf16 v[22:25], v[158:161], v[166:169], v[22:25]
	v_mfma_f32_16x16x32_bf16 v[18:21], v[158:161], v[200:203], v[18:21]
	v_mfma_f32_16x16x32_bf16 v[14:17], v[158:161], v[208:211], v[14:17]
	v_mfma_f32_16x16x32_bf16 v[58:61], v[158:161], v[228:231], v[30:33]
	s_setprio 0
	s_barrier
	s_add_i32 s93, s93, 2
	s_add_u32 s8, s8, 0x100
	s_addc_u32 s9, s9, 0
	s_add_u32 s91, s91, 0x100
	s_addc_u32 s92, s92, 0
	s_cmp_gt_u32 s93, 13
	s_cbranch_scc0 .LBB0_1317
	s_and_b64 vcc, exec, s[18:19]
	s_cbranch_vccz .LBB0_1320
	s_barrier

.LBB0_1463:
	ds_read_b128 v[128:131], v169
	ds_read_b128 v[132:135], v169 offset:1024
	ds_read_b128 v[136:139], v169 offset:2048
	ds_read_b128 v[140:143], v169 offset:3072
	ds_read_b128 v[160:163], v170
	ds_read_b128 v[172:175], v170 offset:1024
	ds_read_b128 v[176:179], v170 offset:2048
	ds_read_b128 v[180:183], v170 offset:3072
	s_add_u32 s18, s16, 0xfff50080
	s_addc_u32 s19, s17, -1
	s_cmp_eq_u32 s45, 40
	s_cselect_b32 s21, s5, s19
	s_cselect_b32 s20, s4, s18
	s_cselect_b32 s19, s15, s44
	s_cselect_b32 s18, s14, s43
	v_lshl_add_u64 v[164:165], s[16:17], 0, v[152:153]
	s_add_i32 m0, s26, 0xc000
	ds_read_b128 v[184:187], v171
	ds_read_b128 v[188:191], v171 offset:1024
	ds_read_b128 v[192:195], v171 offset:2048
	ds_read_b128 v[196:199], v171 offset:3072
	ds_read_b128 v[200:203], v171 offset:4096
	ds_read_b128 v[204:207], v171 offset:5120
	ds_read_b128 v[208:211], v171 offset:6144
	ds_read_b128 v[212:215], v171 offset:7168
	global_load_lds_dwordx4 v[164:165], off
	v_lshl_add_u64 v[164:165], s[16:17], 0, v[154:155]
	s_add_i32 m0, s26, 0xe000
	s_nop 0
	global_load_lds_dwordx4 v[164:165], off
	s_waitcnt vmcnt(8)
	s_waitcnt lgkmcnt(0)
	s_barrier
	s_setprio 1
	v_mfma_f32_16x16x32_bf16 v[124:127], v[128:131], v[184:187], v[124:127]
	v_mfma_f32_16x16x32_bf16 v[120:123], v[136:139], v[184:187], v[120:123]
	v_mfma_f32_16x16x32_bf16 v[116:119], v[128:131], v[192:195], v[116:119]
	v_mfma_f32_16x16x32_bf16 v[108:111], v[136:139], v[192:195], v[108:111]
	v_mfma_f32_16x16x32_bf16 v[92:95], v[128:131], v[200:203], v[92:95]
	v_mfma_f32_16x16x32_bf16 v[88:91], v[136:139], v[200:203], v[88:91]
	v_mfma_f32_16x16x32_bf16 v[84:87], v[128:131], v[208:211], v[84:87]
	v_mfma_f32_16x16x32_bf16 v[80:83], v[136:139], v[208:211], v[80:83]
	v_mfma_f32_16x16x32_bf16 v[124:127], v[132:135], v[188:191], v[124:127]
	v_mfma_f32_16x16x32_bf16 v[120:123], v[140:143], v[188:191], v[120:123]
	v_mfma_f32_16x16x32_bf16 v[116:119], v[132:135], v[196:199], v[116:119]
	v_mfma_f32_16x16x32_bf16 v[108:111], v[140:143], v[196:199], v[108:111]
	v_mfma_f32_16x16x32_bf16 v[92:95], v[132:135], v[204:207], v[92:95]
	v_mfma_f32_16x16x32_bf16 v[88:91], v[140:143], v[204:207], v[88:91]
	v_mfma_f32_16x16x32_bf16 v[84:87], v[132:135], v[212:215], v[84:87]
	v_mfma_f32_16x16x32_bf16 v[80:83], v[140:143], v[212:215], v[80:83]
	v_mfma_f32_16x16x32_bf16 v[112:115], v[160:163], v[184:187], v[112:115]
	v_mfma_f32_16x16x32_bf16 v[104:107], v[176:179], v[184:187], v[104:107]
	v_mfma_f32_16x16x32_bf16 v[100:103], v[160:163], v[192:195], v[100:103]
	v_mfma_f32_16x16x32_bf16 v[96:99], v[176:179], v[192:195], v[96:99]
	v_mfma_f32_16x16x32_bf16 v[76:79], v[160:163], v[200:203], v[76:79]
	v_mfma_f32_16x16x32_bf16 v[72:75], v[176:179], v[200:203], v[72:75]
	v_mfma_f32_16x16x32_bf16 v[68:71], v[160:163], v[208:211], v[68:71]
	v_mfma_f32_16x16x32_bf16 v[64:67], v[176:179], v[208:211], v[64:67]
	v_mfma_f32_16x16x32_bf16 v[112:115], v[172:175], v[188:191], v[112:115]
	v_mfma_f32_16x16x32_bf16 v[104:107], v[180:183], v[188:191], v[104:107]
	v_mfma_f32_16x16x32_bf16 v[100:103], v[172:175], v[196:199], v[100:103]
	v_mfma_f32_16x16x32_bf16 v[96:99], v[180:183], v[196:199], v[96:99]
	v_mfma_f32_16x16x32_bf16 v[76:79], v[172:175], v[204:207], v[76:79]
	v_mfma_f32_16x16x32_bf16 v[72:75], v[180:183], v[204:207], v[72:75]
	v_mfma_f32_16x16x32_bf16 v[68:71], v[172:175], v[212:215], v[68:71]
	v_mfma_f32_16x16x32_bf16 v[64:67], v[180:183], v[212:215], v[64:67]
	s_setprio 0
	s_barrier
	s_add_i32 s46, s37, s25
	v_lshl_add_u64 v[164:165], s[18:19], 0, v[146:147]
	s_mov_b32 m0, s46
	ds_read_b128 v[184:187], v171 offset:16384
	ds_read_b128 v[188:191], v171 offset:17408
	ds_read_b128 v[192:195], v171 offset:18432
	ds_read_b128 v[196:199], v171 offset:19456
	ds_read_b128 v[200:203], v171 offset:20480
	ds_read_b128 v[204:207], v171 offset:21504
	ds_read_b128 v[208:211], v171 offset:22528
	ds_read_b128 v[212:215], v171 offset:23552
	global_load_lds_dwordx4 v[164:165], off
	s_add_i32 m0, s46, 0x2000
	s_add_u32 s46, s18, 0xb0000
	v_lshl_add_u64 v[216:217], s[18:19], 0, v[150:151]
	s_addc_u32 s47, s19, 0
	s_add_i32 s48, s38, s25
	global_load_lds_dwordx4 v[216:217], off
	v_lshl_add_u64 v[218:219], s[46:47], 0, v[146:147]
	s_mov_b32 m0, s48
	v_lshl_add_u64 v[220:221], s[20:21], 0, v[148:149]
	global_load_lds_dwordx4 v[218:219], off
	v_lshl_add_u64 v[218:219], s[46:47], 0, v[150:151]
	s_add_i32 m0, s48, 0x2000
	s_nop 0
	global_load_lds_dwordx4 v[218:219], off
	v_lshl_add_u64 v[218:219], s[20:21], 0, v[144:145]
	s_mov_b32 m0, s26
	s_nop 0
	global_load_lds_dwordx4 v[218:219], off
	s_mov_b32 m0, s27
	s_nop 0
	global_load_lds_dwordx4 v[220:221], off
	s_waitcnt vmcnt(8)
	s_waitcnt lgkmcnt(0)
	s_barrier
	s_setprio 1
	v_mfma_f32_16x16x32_bf16 v[60:63], v[128:131], v[184:187], v[60:63]
	v_mfma_f32_16x16x32_bf16 v[56:59], v[136:139], v[184:187], v[56:59]
	v_mfma_f32_16x16x32_bf16 v[52:55], v[128:131], v[192:195], v[52:55]
	v_mfma_f32_16x16x32_bf16 v[48:51], v[136:139], v[192:195], v[48:51]
	v_mfma_f32_16x16x32_bf16 v[28:31], v[128:131], v[200:203], v[28:31]
	v_mfma_f32_16x16x32_bf16 v[24:27], v[136:139], v[200:203], v[24:27]
	v_mfma_f32_16x16x32_bf16 v[20:23], v[128:131], v[208:211], v[20:23]
	v_mfma_f32_16x16x32_bf16 v[16:19], v[136:139], v[208:211], v[16:19]
	v_mfma_f32_16x16x32_bf16 v[60:63], v[132:135], v[188:191], v[60:63]
	v_mfma_f32_16x16x32_bf16 v[56:59], v[140:143], v[188:191], v[56:59]
	v_mfma_f32_16x16x32_bf16 v[52:55], v[132:135], v[196:199], v[52:55]
	v_mfma_f32_16x16x32_bf16 v[48:51], v[140:143], v[196:199], v[48:51]
	v_mfma_f32_16x16x32_bf16 v[28:31], v[132:135], v[204:207], v[28:31]
	v_mfma_f32_16x16x32_bf16 v[24:27], v[140:143], v[204:207], v[24:27]
	v_mfma_f32_16x16x32_bf16 v[20:23], v[132:135], v[212:215], v[20:23]
	v_mfma_f32_16x16x32_bf16 v[16:19], v[140:143], v[212:215], v[16:19]
	v_mfma_f32_16x16x32_bf16 v[44:47], v[160:163], v[184:187], v[44:47]
	v_mfma_f32_16x16x32_bf16 v[40:43], v[176:179], v[184:187], v[40:43]
	v_mfma_f32_16x16x32_bf16 v[36:39], v[160:163], v[192:195], v[36:39]
	v_mfma_f32_16x16x32_bf16 v[32:35], v[176:179], v[192:195], v[32:35]
	v_mfma_f32_16x16x32_bf16 v[12:15], v[160:163], v[200:203], v[12:15]
	v_mfma_f32_16x16x32_bf16 v[8:11], v[176:179], v[200:203], v[8:11]
	v_mfma_f32_16x16x32_bf16 v[4:7], v[160:163], v[208:211], v[4:7]
	v_mfma_f32_16x16x32_bf16 v[0:3], v[176:179], v[208:211], v[0:3]
	v_mfma_f32_16x16x32_bf16 v[44:47], v[172:175], v[188:191], v[44:47]
	v_mfma_f32_16x16x32_bf16 v[40:43], v[180:183], v[188:191], v[40:43]
	v_mfma_f32_16x16x32_bf16 v[36:39], v[172:175], v[196:199], v[36:39]
	v_mfma_f32_16x16x32_bf16 v[32:35], v[180:183], v[196:199], v[32:35]
	v_mfma_f32_16x16x32_bf16 v[12:15], v[172:175], v[204:207], v[12:15]
	v_mfma_f32_16x16x32_bf16 v[8:11], v[180:183], v[204:207], v[8:11]
	v_mfma_f32_16x16x32_bf16 v[4:7], v[172:175], v[212:215], v[4:7]
	v_mfma_f32_16x16x32_bf16 v[0:3], v[180:183], v[212:215], v[0:3]
	s_setprio 0
	s_barrier
	s_add_i32 s46, 0, 0x18000
	s_add_i32 s47, 0, 0x1c000
	v_add_u32_e32 v140, s46, v167
	v_add_u32_e32 v180, s47, v167
	ds_read_b128 v[128:131], v140
	ds_read_b128 v[132:135], v140 offset:1024
	ds_read_b128 v[136:139], v140 offset:2048
	ds_read_b128 v[140:143], v140 offset:3072
	ds_read_b128 v[160:163], v180
	ds_read_b128 v[172:175], v180 offset:1024
	ds_read_b128 v[176:179], v180 offset:2048
	ds_read_b128 v[180:183], v180 offset:3072
	s_add_u32 s20, s20, 0xb0000
	s_addc_u32 s21, s21, 0
	s_mov_b32 m0, s28
	v_lshl_add_u64 v[222:223], s[20:21], 0, v[144:145]
	ds_read_b128 v[184:187], v171 offset:32768
	ds_read_b128 v[188:191], v171 offset:33792
	ds_read_b128 v[192:195], v171 offset:34816
	ds_read_b128 v[196:199], v171 offset:35840
	ds_read_b128 v[200:203], v171 offset:36864
	ds_read_b128 v[204:207], v171 offset:37888
	ds_read_b128 v[208:211], v171 offset:38912
	ds_read_b128 v[212:215], v171 offset:39936
	global_load_lds_dwordx4 v[222:223], off
	v_lshl_add_u64 v[222:223], s[20:21], 0, v[148:149]
	s_mov_b32 m0, s29
	s_nop 0
	global_load_lds_dwordx4 v[222:223], off
	s_waitcnt vmcnt(8)
	s_waitcnt lgkmcnt(0)
	s_barrier
	s_setprio 1
	v_mfma_f32_16x16x32_bf16 v[124:127], v[128:131], v[184:187], v[124:127]
	v_mfma_f32_16x16x32_bf16 v[120:123], v[136:139], v[184:187], v[120:123]
	v_mfma_f32_16x16x32_bf16 v[116:119], v[128:131], v[192:195], v[116:119]
	v_mfma_f32_16x16x32_bf16 v[108:111], v[136:139], v[192:195], v[108:111]
	v_mfma_f32_16x16x32_bf16 v[92:95], v[128:131], v[200:203], v[92:95]
	v_mfma_f32_16x16x32_bf16 v[88:91], v[136:139], v[200:203], v[88:91]
	v_mfma_f32_16x16x32_bf16 v[84:87], v[128:131], v[208:211], v[84:87]
	v_mfma_f32_16x16x32_bf16 v[80:83], v[136:139], v[208:211], v[80:83]
	v_mfma_f32_16x16x32_bf16 v[124:127], v[132:135], v[188:191], v[124:127]
	v_mfma_f32_16x16x32_bf16 v[120:123], v[140:143], v[188:191], v[120:123]
	v_mfma_f32_16x16x32_bf16 v[116:119], v[132:135], v[196:199], v[116:119]
	v_mfma_f32_16x16x32_bf16 v[108:111], v[140:143], v[196:199], v[108:111]
	v_mfma_f32_16x16x32_bf16 v[92:95], v[132:135], v[204:207], v[92:95]
	v_mfma_f32_16x16x32_bf16 v[88:91], v[140:143], v[204:207], v[88:91]
	v_mfma_f32_16x16x32_bf16 v[84:87], v[132:135], v[212:215], v[84:87]
	v_mfma_f32_16x16x32_bf16 v[80:83], v[140:143], v[212:215], v[80:83]
	v_mfma_f32_16x16x32_bf16 v[112:115], v[160:163], v[184:187], v[112:115]
	v_mfma_f32_16x16x32_bf16 v[104:107], v[176:179], v[184:187], v[104:107]
	v_mfma_f32_16x16x32_bf16 v[100:103], v[160:163], v[192:195], v[100:103]
	v_mfma_f32_16x16x32_bf16 v[96:99], v[176:179], v[192:195], v[96:99]
	v_mfma_f32_16x16x32_bf16 v[76:79], v[160:163], v[200:203], v[76:79]
	v_mfma_f32_16x16x32_bf16 v[72:75], v[176:179], v[200:203], v[72:75]
	v_mfma_f32_16x16x32_bf16 v[68:71], v[160:163], v[208:211], v[68:71]
	v_mfma_f32_16x16x32_bf16 v[64:67], v[176:179], v[208:211], v[64:67]
	v_mfma_f32_16x16x32_bf16 v[112:115], v[172:175], v[188:191], v[112:115]
	v_mfma_f32_16x16x32_bf16 v[104:107], v[180:183], v[188:191], v[104:107]
	v_mfma_f32_16x16x32_bf16 v[100:103], v[172:175], v[196:199], v[100:103]
	v_mfma_f32_16x16x32_bf16 v[96:99], v[180:183], v[196:199], v[96:99]
	v_mfma_f32_16x16x32_bf16 v[76:79], v[172:175], v[204:207], v[76:79]
	v_mfma_f32_16x16x32_bf16 v[72:75], v[180:183], v[204:207], v[72:75]
	v_mfma_f32_16x16x32_bf16 v[68:71], v[172:175], v[212:215], v[68:71]
	v_mfma_f32_16x16x32_bf16 v[64:67], v[180:183], v[212:215], v[64:67]
	s_setprio 0
	s_barrier
	s_add_i32 s20, s46, s25
	v_lshl_add_u64 v[164:165], v[164:165], 0, s[8:9]
	s_mov_b32 m0, s20
	ds_read_b128 v[184:187], v171 offset:49152
	ds_read_b128 v[188:191], v171 offset:50176
	ds_read_b128 v[192:195], v171 offset:51200
	ds_read_b128 v[196:199], v171 offset:52224
	ds_read_b128 v[200:203], v171 offset:53248
	ds_read_b128 v[204:207], v171 offset:54272
	ds_read_b128 v[208:211], v171 offset:55296
	ds_read_b128 v[212:215], v171 offset:56320
	global_load_lds_dwordx4 v[164:165], off
	s_add_i32 m0, s20, 0x2000
	s_add_u32 s18, s18, 0xb0080
	v_lshl_add_u64 v[164:165], v[216:217], 0, s[8:9]
	s_addc_u32 s19, s19, 0
	s_add_i32 s20, s47, s25
	global_load_lds_dwordx4 v[164:165], off
	v_lshl_add_u64 v[164:165], s[18:19], 0, v[146:147]
	s_mov_b32 m0, s20
	s_nop 0
	global_load_lds_dwordx4 v[164:165], off
	v_lshl_add_u64 v[164:165], s[18:19], 0, v[150:151]
	s_add_i32 m0, s20, 0x2000
	s_nop 0
	global_load_lds_dwordx4 v[164:165], off
	v_lshl_add_u64 v[164:165], v[218:219], 0, s[8:9]
	s_mov_b32 m0, s35
	s_nop 0
	global_load_lds_dwordx4 v[164:165], off
	v_lshl_add_u64 v[164:165], v[220:221], 0, s[8:9]
	s_mov_b32 m0, s36
	s_nop 0
	global_load_lds_dwordx4 v[164:165], off
	s_waitcnt vmcnt(8)
	s_waitcnt lgkmcnt(0)
	s_barrier
	s_setprio 1
	v_mfma_f32_16x16x32_bf16 v[60:63], v[128:131], v[184:187], v[60:63]
	v_mfma_f32_16x16x32_bf16 v[56:59], v[136:139], v[184:187], v[56:59]
	v_mfma_f32_16x16x32_bf16 v[52:55], v[128:131], v[192:195], v[52:55]
	v_mfma_f32_16x16x32_bf16 v[48:51], v[136:139], v[192:195], v[48:51]
	v_mfma_f32_16x16x32_bf16 v[28:31], v[128:131], v[200:203], v[28:31]
	v_mfma_f32_16x16x32_bf16 v[24:27], v[136:139], v[200:203], v[24:27]
	v_mfma_f32_16x16x32_bf16 v[20:23], v[128:131], v[208:211], v[20:23]
	v_mfma_f32_16x16x32_bf16 v[16:19], v[136:139], v[208:211], v[16:19]
	v_mfma_f32_16x16x32_bf16 v[60:63], v[132:135], v[188:191], v[60:63]
	v_mfma_f32_16x16x32_bf16 v[56:59], v[140:143], v[188:191], v[56:59]
	v_mfma_f32_16x16x32_bf16 v[52:55], v[132:135], v[196:199], v[52:55]
	v_mfma_f32_16x16x32_bf16 v[48:51], v[140:143], v[196:199], v[48:51]
	v_mfma_f32_16x16x32_bf16 v[28:31], v[132:135], v[204:207], v[28:31]
	v_mfma_f32_16x16x32_bf16 v[24:27], v[140:143], v[204:207], v[24:27]
	v_mfma_f32_16x16x32_bf16 v[20:23], v[132:135], v[212:215], v[20:23]
	v_mfma_f32_16x16x32_bf16 v[16:19], v[140:143], v[212:215], v[16:19]
	v_mfma_f32_16x16x32_bf16 v[44:47], v[160:163], v[184:187], v[44:47]
	v_mfma_f32_16x16x32_bf16 v[40:43], v[176:179], v[184:187], v[40:43]
	v_mfma_f32_16x16x32_bf16 v[36:39], v[160:163], v[192:195], v[36:39]
	v_mfma_f32_16x16x32_bf16 v[32:35], v[176:179], v[192:195], v[32:35]
	v_mfma_f32_16x16x32_bf16 v[12:15], v[160:163], v[200:203], v[12:15]
	v_mfma_f32_16x16x32_bf16 v[8:11], v[176:179], v[200:203], v[8:11]
	v_mfma_f32_16x16x32_bf16 v[4:7], v[160:163], v[208:211], v[4:7]
	v_mfma_f32_16x16x32_bf16 v[0:3], v[176:179], v[208:211], v[0:3]
	v_mfma_f32_16x16x32_bf16 v[44:47], v[172:175], v[188:191], v[44:47]
	v_mfma_f32_16x16x32_bf16 v[40:43], v[180:183], v[188:191], v[40:43]
	v_mfma_f32_16x16x32_bf16 v[36:39], v[172:175], v[196:199], v[36:39]
	v_mfma_f32_16x16x32_bf16 v[32:35], v[180:183], v[196:199], v[32:35]
	v_mfma_f32_16x16x32_bf16 v[12:15], v[172:175], v[204:207], v[12:15]
	v_mfma_f32_16x16x32_bf16 v[8:11], v[180:183], v[204:207], v[8:11]
	v_mfma_f32_16x16x32_bf16 v[4:7], v[172:175], v[212:215], v[4:7]
	v_mfma_f32_16x16x32_bf16 v[0:3], v[180:183], v[212:215], v[0:3]
	s_setprio 0
	s_barrier
	s_add_i32 s45, s45, 2
	s_add_u32 s16, s16, 0x100
	s_addc_u32 s17, s17, 0
	s_add_u32 s43, s43, 0x100
	s_addc_u32 s44, s44, 0
	s_cmp_gt_u32 s45, 41
	s_cbranch_scc0 .LBB0_1463
	s_and_b64 vcc, exec, s[12:13]
	s_cbranch_vccz .LBB0_1466
	s_barrier
